# B epilogue V-transposed columns: lane-quad transpose turns four 2-byte stores per fragment into one 8-byte store
# baseline (speedup 1.0000x reference)
.LBB0_372:
	s_add_u32 s4, s2, 0xfffc0080
	s_addc_u32 s5, s3, -1
	s_add_i32 s36, 0, 0x10000
	v_add_u32_e32 v145, s36, v143
	ds_read_b128 v[138:141], v145
	ds_read_b128 v[146:149], v145 offset:1024
	ds_read_b128 v[150:153], v145 offset:2048
	ds_read_b128 v[154:157], v145 offset:3072
	s_cmp_eq_u32 s35, 12
	s_cselect_b32 s7, s10, s5
	s_cselect_b32 s6, s11, s4
	s_cselect_b32 s5, s13, s23
	s_cselect_b32 s4, s15, s22
	v_lshl_add_u64 v[186:187], s[2:3], 0, v[134:135]
	s_add_i32 m0, s25, 0xc000
	ds_read_b128 v[158:161], v144
	ds_read_b128 v[162:165], v144 offset:1024
	ds_read_b128 v[166:169], v144 offset:2048
	ds_read_b128 v[170:173], v144 offset:3072
	ds_read_b128 v[174:177], v144 offset:4096
	ds_read_b128 v[178:181], v144 offset:5120
	ds_read_b128 v[182:185], v144 offset:6144
	ds_read_b128 v[190:193], v144 offset:7168
	global_load_lds_dwordx4 v[186:187], off
	v_lshl_add_u64 v[186:187], s[2:3], 0, v[136:137]
	s_add_i32 m0, s25, 0xe000
	s_nop 0
	global_load_lds_dwordx4 v[186:187], off
	s_waitcnt lgkmcnt(8)
	s_barrier
	s_waitcnt lgkmcnt(0)
	s_setprio 1
	s_waitcnt lgkmcnt(0)
	v_mfma_f32_16x16x32_bf16 v[124:127], v[138:141], v[158:161], v[124:127]
	v_mfma_f32_16x16x32_bf16 v[120:123], v[150:153], v[158:161], v[120:123]
	v_mfma_f32_16x16x32_bf16 v[108:111], v[138:141], v[166:169], v[108:111]
	v_mfma_f32_16x16x32_bf16 v[104:107], v[150:153], v[166:169], v[104:107]
	v_mfma_f32_16x16x32_bf16 v[92:95], v[138:141], v[174:177], v[92:95]
	v_mfma_f32_16x16x32_bf16 v[88:91], v[150:153], v[174:177], v[88:91]
	v_mfma_f32_16x16x32_bf16 v[76:79], v[138:141], v[182:185], v[76:79]
	v_mfma_f32_16x16x32_bf16 v[72:75], v[150:153], v[182:185], v[72:75]
	v_mfma_f32_16x16x32_bf16 v[124:127], v[146:149], v[162:165], v[124:127]
	v_mfma_f32_16x16x32_bf16 v[120:123], v[154:157], v[162:165], v[120:123]
	v_mfma_f32_16x16x32_bf16 v[108:111], v[146:149], v[170:173], v[108:111]
	v_mfma_f32_16x16x32_bf16 v[104:107], v[154:157], v[170:173], v[104:107]
	v_mfma_f32_16x16x32_bf16 v[92:95], v[146:149], v[178:181], v[92:95]
	v_mfma_f32_16x16x32_bf16 v[88:91], v[154:157], v[178:181], v[88:91]
	v_mfma_f32_16x16x32_bf16 v[76:79], v[146:149], v[190:193], v[76:79]
	v_mfma_f32_16x16x32_bf16 v[72:75], v[154:157], v[190:193], v[72:75]
	s_setprio 0
	s_barrier
	s_add_i32 s38, 0, 0x14000
	s_add_i32 s36, s36, s24
	v_add_u32_e32 v145, s38, v143
	v_lshl_add_u64 v[186:187], s[4:5], 0, v[130:131]
	s_mov_b32 m0, s36
	ds_read_b128 v[194:197], v145
	ds_read_b128 v[198:201], v145 offset:1024
	ds_read_b128 v[216:219], v145 offset:2048
	ds_read_b128 v[220:223], v145 offset:3072
	global_load_lds_dwordx4 v[186:187], off
	v_lshl_add_u64 v[202:203], s[4:5], 0, v[128:129]
	s_add_i32 m0, s36, 0x2000
	s_nop 0
	global_load_lds_dwordx4 v[202:203], off
	s_barrier
	s_waitcnt lgkmcnt(0)
	s_setprio 1
	s_waitcnt lgkmcnt(0)
	v_mfma_f32_16x16x32_bf16 v[116:119], v[194:197], v[158:161], v[116:119]
	v_mfma_f32_16x16x32_bf16 v[112:115], v[216:219], v[158:161], v[112:115]
	v_mfma_f32_16x16x32_bf16 v[100:103], v[194:197], v[166:169], v[100:103]
	v_mfma_f32_16x16x32_bf16 v[96:99], v[216:219], v[166:169], v[96:99]
	v_mfma_f32_16x16x32_bf16 v[84:87], v[194:197], v[174:177], v[84:87]
	v_mfma_f32_16x16x32_bf16 v[80:83], v[216:219], v[174:177], v[80:83]
	v_mfma_f32_16x16x32_bf16 v[68:71], v[194:197], v[182:185], v[68:71]
	v_mfma_f32_16x16x32_bf16 v[64:67], v[216:219], v[182:185], v[64:67]
	v_mfma_f32_16x16x32_bf16 v[116:119], v[198:201], v[162:165], v[116:119]
	v_mfma_f32_16x16x32_bf16 v[112:115], v[220:223], v[162:165], v[112:115]
	v_mfma_f32_16x16x32_bf16 v[100:103], v[198:201], v[170:173], v[100:103]
	v_mfma_f32_16x16x32_bf16 v[96:99], v[220:223], v[170:173], v[96:99]
	v_mfma_f32_16x16x32_bf16 v[84:87], v[198:201], v[178:181], v[84:87]
	v_mfma_f32_16x16x32_bf16 v[80:83], v[220:223], v[178:181], v[80:83]
	v_mfma_f32_16x16x32_bf16 v[68:71], v[198:201], v[190:193], v[68:71]
	v_mfma_f32_16x16x32_bf16 v[64:67], v[220:223], v[190:193], v[64:67]
	s_setprio 0
	s_mov_b32 m0, s25
	v_lshl_add_u64 v[224:225], s[6:7], 0, v[130:131]
	s_barrier
	ds_read_b128 v[158:161], v144 offset:16384
	ds_read_b128 v[162:165], v144 offset:17408
	ds_read_b128 v[166:169], v144 offset:18432
	ds_read_b128 v[170:173], v144 offset:19456
	ds_read_b128 v[174:177], v144 offset:20480
	ds_read_b128 v[178:181], v144 offset:21504
	ds_read_b128 v[182:185], v144 offset:22528
	ds_read_b128 v[190:193], v144 offset:23552
	global_load_lds_dwordx4 v[224:225], off
	v_lshl_add_u64 v[226:227], s[6:7], 0, v[128:129]
	s_mov_b32 m0, s26
	s_nop 0
	global_load_lds_dwordx4 v[226:227], off
	s_barrier
	s_waitcnt lgkmcnt(0)
	s_setprio 1
	s_waitcnt lgkmcnt(0)
	v_mfma_f32_16x16x32_bf16 v[60:63], v[138:141], v[158:161], v[60:63]
	v_mfma_f32_16x16x32_bf16 v[56:59], v[150:153], v[158:161], v[56:59]
	v_mfma_f32_16x16x32_bf16 v[44:47], v[138:141], v[166:169], v[44:47]
	v_mfma_f32_16x16x32_bf16 v[40:43], v[150:153], v[166:169], v[40:43]
	v_mfma_f32_16x16x32_bf16 v[28:31], v[138:141], v[174:177], v[28:31]
	v_mfma_f32_16x16x32_bf16 v[24:27], v[150:153], v[174:177], v[24:27]
	v_mfma_f32_16x16x32_bf16 v[12:15], v[138:141], v[182:185], v[12:15]
	v_mfma_f32_16x16x32_bf16 v[8:11], v[150:153], v[182:185], v[8:11]
	v_mfma_f32_16x16x32_bf16 v[60:63], v[146:149], v[162:165], v[60:63]
	v_mfma_f32_16x16x32_bf16 v[56:59], v[154:157], v[162:165], v[56:59]
	v_mfma_f32_16x16x32_bf16 v[44:47], v[146:149], v[170:173], v[44:47]
	v_mfma_f32_16x16x32_bf16 v[40:43], v[154:157], v[170:173], v[40:43]
	v_mfma_f32_16x16x32_bf16 v[28:31], v[146:149], v[178:181], v[28:31]
	v_mfma_f32_16x16x32_bf16 v[24:27], v[154:157], v[178:181], v[24:27]
	v_mfma_f32_16x16x32_bf16 v[12:15], v[146:149], v[190:193], v[12:15]
	v_mfma_f32_16x16x32_bf16 v[8:11], v[154:157], v[190:193], v[8:11]
	s_setprio 0
	s_barrier
	s_add_u32 s36, s4, 0x40000
	s_addc_u32 s37, s5, 0
	s_add_i32 s38, s38, s24
	v_lshl_add_u64 v[138:139], s[36:37], 0, v[130:131]
	s_mov_b32 m0, s38
	s_nop 0
	global_load_lds_dwordx4 v[138:139], off
	v_lshl_add_u64 v[138:139], s[36:37], 0, v[128:129]
	s_add_i32 m0, s38, 0x2000
	s_nop 0
	global_load_lds_dwordx4 v[138:139], off
	s_waitcnt vmcnt(6)
	s_barrier
	s_setprio 1
	v_mfma_f32_16x16x32_bf16 v[52:55], v[194:197], v[158:161], v[52:55]
	v_mfma_f32_16x16x32_bf16 v[48:51], v[216:219], v[158:161], v[48:51]
	v_mfma_f32_16x16x32_bf16 v[36:39], v[194:197], v[166:169], v[36:39]
	v_mfma_f32_16x16x32_bf16 v[32:35], v[216:219], v[166:169], v[32:35]
	v_mfma_f32_16x16x32_bf16 v[20:23], v[194:197], v[174:177], v[20:23]
	v_mfma_f32_16x16x32_bf16 v[16:19], v[216:219], v[174:177], v[16:19]
	v_mfma_f32_16x16x32_bf16 v[4:7], v[194:197], v[182:185], v[4:7]
	v_mfma_f32_16x16x32_bf16 v[0:3], v[216:219], v[182:185], v[0:3]
	v_mfma_f32_16x16x32_bf16 v[52:55], v[198:201], v[162:165], v[52:55]
	v_mfma_f32_16x16x32_bf16 v[48:51], v[220:223], v[162:165], v[48:51]
	v_mfma_f32_16x16x32_bf16 v[36:39], v[198:201], v[170:173], v[36:39]
	v_mfma_f32_16x16x32_bf16 v[32:35], v[220:223], v[170:173], v[32:35]
	v_mfma_f32_16x16x32_bf16 v[20:23], v[198:201], v[178:181], v[20:23]
	v_mfma_f32_16x16x32_bf16 v[16:19], v[220:223], v[178:181], v[16:19]
	v_mfma_f32_16x16x32_bf16 v[4:7], v[198:201], v[190:193], v[4:7]
	v_mfma_f32_16x16x32_bf16 v[0:3], v[220:223], v[190:193], v[0:3]
	s_setprio 0
	s_add_i32 s36, 0, 0x18000
	v_add_u32_e32 v145, s36, v143
	s_barrier
	ds_read_b128 v[138:141], v145
	ds_read_b128 v[146:149], v145 offset:1024
	ds_read_b128 v[150:153], v145 offset:2048
	ds_read_b128 v[154:157], v145 offset:3072
	s_add_u32 s6, s6, 0x40000
	s_addc_u32 s7, s7, 0
	s_mov_b32 m0, s27
	v_lshl_add_u64 v[194:195], s[6:7], 0, v[130:131]
	ds_read_b128 v[158:161], v144 offset:32768
	ds_read_b128 v[162:165], v144 offset:33792
	ds_read_b128 v[166:169], v144 offset:34816
	ds_read_b128 v[170:173], v144 offset:35840
	ds_read_b128 v[174:177], v144 offset:36864
	ds_read_b128 v[178:181], v144 offset:37888
	ds_read_b128 v[182:185], v144 offset:38912
	ds_read_b128 v[190:193], v144 offset:39936
	global_load_lds_dwordx4 v[194:195], off
	v_lshl_add_u64 v[194:195], s[6:7], 0, v[128:129]
	s_mov_b32 m0, s28
	s_nop 0
	global_load_lds_dwordx4 v[194:195], off
	s_waitcnt lgkmcnt(8)
	s_barrier
	s_waitcnt lgkmcnt(0)
	s_setprio 1
	s_waitcnt lgkmcnt(0)
	v_mfma_f32_16x16x32_bf16 v[124:127], v[138:141], v[158:161], v[124:127]
	v_mfma_f32_16x16x32_bf16 v[120:123], v[150:153], v[158:161], v[120:123]
	v_mfma_f32_16x16x32_bf16 v[108:111], v[138:141], v[166:169], v[108:111]
	v_mfma_f32_16x16x32_bf16 v[104:107], v[150:153], v[166:169], v[104:107]
	v_mfma_f32_16x16x32_bf16 v[92:95], v[138:141], v[174:177], v[92:95]
	v_mfma_f32_16x16x32_bf16 v[88:91], v[150:153], v[174:177], v[88:91]
	v_mfma_f32_16x16x32_bf16 v[76:79], v[138:141], v[182:185], v[76:79]
	v_mfma_f32_16x16x32_bf16 v[72:75], v[150:153], v[182:185], v[72:75]
	v_mfma_f32_16x16x32_bf16 v[124:127], v[146:149], v[162:165], v[124:127]
	v_mfma_f32_16x16x32_bf16 v[120:123], v[154:157], v[162:165], v[120:123]
	v_mfma_f32_16x16x32_bf16 v[108:111], v[146:149], v[170:173], v[108:111]
	v_mfma_f32_16x16x32_bf16 v[104:107], v[154:157], v[170:173], v[104:107]
	v_mfma_f32_16x16x32_bf16 v[92:95], v[146:149], v[178:181], v[92:95]
	v_mfma_f32_16x16x32_bf16 v[88:91], v[154:157], v[178:181], v[88:91]
	v_mfma_f32_16x16x32_bf16 v[76:79], v[146:149], v[190:193], v[76:79]
	v_mfma_f32_16x16x32_bf16 v[72:75], v[154:157], v[190:193], v[72:75]
	s_setprio 0
	s_barrier
	s_add_i32 s6, 0, 0x1c000
	s_add_i32 s7, s36, s24
	v_add_u32_e32 v145, s6, v143
	v_lshl_add_u64 v[186:187], v[186:187], 0, s[92:93]
	s_mov_b32 m0, s7
	ds_read_b128 v[194:197], v145
	ds_read_b128 v[198:201], v145 offset:1024
	ds_read_b128 v[216:219], v145 offset:2048
	ds_read_b128 v[220:223], v145 offset:3072
	global_load_lds_dwordx4 v[186:187], off
	v_lshl_add_u64 v[186:187], v[202:203], 0, s[92:93]
	s_add_i32 m0, s7, 0x2000
	s_nop 0
	global_load_lds_dwordx4 v[186:187], off
	s_barrier
	s_waitcnt lgkmcnt(0)
	s_setprio 1
	s_waitcnt lgkmcnt(0)
	v_mfma_f32_16x16x32_bf16 v[116:119], v[194:197], v[158:161], v[116:119]
	v_mfma_f32_16x16x32_bf16 v[112:115], v[216:219], v[158:161], v[112:115]
	v_mfma_f32_16x16x32_bf16 v[100:103], v[194:197], v[166:169], v[100:103]
	v_mfma_f32_16x16x32_bf16 v[96:99], v[216:219], v[166:169], v[96:99]
	v_mfma_f32_16x16x32_bf16 v[84:87], v[194:197], v[174:177], v[84:87]
	v_mfma_f32_16x16x32_bf16 v[80:83], v[216:219], v[174:177], v[80:83]
	v_mfma_f32_16x16x32_bf16 v[68:71], v[194:197], v[182:185], v[68:71]
	v_mfma_f32_16x16x32_bf16 v[64:67], v[216:219], v[182:185], v[64:67]
	v_mfma_f32_16x16x32_bf16 v[116:119], v[198:201], v[162:165], v[116:119]
	v_mfma_f32_16x16x32_bf16 v[112:115], v[220:223], v[162:165], v[112:115]
	v_mfma_f32_16x16x32_bf16 v[100:103], v[198:201], v[170:173], v[100:103]
	v_mfma_f32_16x16x32_bf16 v[96:99], v[220:223], v[170:173], v[96:99]
	v_mfma_f32_16x16x32_bf16 v[84:87], v[198:201], v[178:181], v[84:87]
	v_mfma_f32_16x16x32_bf16 v[80:83], v[220:223], v[178:181], v[80:83]
	v_mfma_f32_16x16x32_bf16 v[68:71], v[198:201], v[190:193], v[68:71]
	v_mfma_f32_16x16x32_bf16 v[64:67], v[220:223], v[190:193], v[64:67]
	s_setprio 0
	s_mov_b32 m0, s31
	v_lshl_add_u64 v[186:187], v[224:225], 0, s[92:93]
	s_barrier
	ds_read_b128 v[158:161], v144 offset:49152
	ds_read_b128 v[162:165], v144 offset:50176
	ds_read_b128 v[166:169], v144 offset:51200
	ds_read_b128 v[170:173], v144 offset:52224
	ds_read_b128 v[174:177], v144 offset:53248
	ds_read_b128 v[178:181], v144 offset:54272
	ds_read_b128 v[182:185], v144 offset:55296
	ds_read_b128 v[190:193], v144 offset:56320
	global_load_lds_dwordx4 v[186:187], off
	v_lshl_add_u64 v[186:187], v[226:227], 0, s[92:93]
	s_mov_b32 m0, s33
	s_nop 0
	global_load_lds_dwordx4 v[186:187], off
	s_barrier
	s_waitcnt lgkmcnt(0)
	s_setprio 1
	s_waitcnt lgkmcnt(0)
	v_mfma_f32_16x16x32_bf16 v[60:63], v[138:141], v[158:161], v[60:63]
	v_mfma_f32_16x16x32_bf16 v[56:59], v[150:153], v[158:161], v[56:59]
	v_mfma_f32_16x16x32_bf16 v[44:47], v[138:141], v[166:169], v[44:47]
	v_mfma_f32_16x16x32_bf16 v[40:43], v[150:153], v[166:169], v[40:43]
	v_mfma_f32_16x16x32_bf16 v[28:31], v[138:141], v[174:177], v[28:31]
	v_mfma_f32_16x16x32_bf16 v[24:27], v[150:153], v[174:177], v[24:27]
	v_mfma_f32_16x16x32_bf16 v[12:15], v[138:141], v[182:185], v[12:15]
	v_mfma_f32_16x16x32_bf16 v[8:11], v[150:153], v[182:185], v[8:11]
	v_mfma_f32_16x16x32_bf16 v[60:63], v[146:149], v[162:165], v[60:63]
	v_mfma_f32_16x16x32_bf16 v[56:59], v[154:157], v[162:165], v[56:59]
	v_mfma_f32_16x16x32_bf16 v[44:47], v[146:149], v[170:173], v[44:47]
	v_mfma_f32_16x16x32_bf16 v[40:43], v[154:157], v[170:173], v[40:43]
	v_mfma_f32_16x16x32_bf16 v[28:31], v[146:149], v[178:181], v[28:31]
	v_mfma_f32_16x16x32_bf16 v[24:27], v[154:157], v[178:181], v[24:27]
	v_mfma_f32_16x16x32_bf16 v[12:15], v[146:149], v[190:193], v[12:15]
	v_mfma_f32_16x16x32_bf16 v[8:11], v[154:157], v[190:193], v[8:11]
	s_setprio 0
	s_barrier
	s_add_u32 s4, s4, 0x40080
	s_addc_u32 s5, s5, 0
	s_add_i32 s6, s6, s24
	v_lshl_add_u64 v[138:139], s[4:5], 0, v[130:131]
	s_mov_b32 m0, s6
	s_nop 0
	global_load_lds_dwordx4 v[138:139], off
	v_lshl_add_u64 v[138:139], s[4:5], 0, v[128:129]
	s_add_i32 m0, s6, 0x2000
	s_nop 0
	global_load_lds_dwordx4 v[138:139], off
	s_waitcnt vmcnt(6)
	s_barrier
	s_setprio 1
	v_mfma_f32_16x16x32_bf16 v[52:55], v[194:197], v[158:161], v[52:55]
	v_mfma_f32_16x16x32_bf16 v[48:51], v[216:219], v[158:161], v[48:51]
	v_mfma_f32_16x16x32_bf16 v[36:39], v[194:197], v[166:169], v[36:39]
	v_mfma_f32_16x16x32_bf16 v[32:35], v[216:219], v[166:169], v[32:35]
	v_mfma_f32_16x16x32_bf16 v[20:23], v[194:197], v[174:177], v[20:23]
	v_mfma_f32_16x16x32_bf16 v[16:19], v[216:219], v[174:177], v[16:19]
	v_mfma_f32_16x16x32_bf16 v[4:7], v[194:197], v[182:185], v[4:7]
	v_mfma_f32_16x16x32_bf16 v[0:3], v[216:219], v[182:185], v[0:3]
	v_mfma_f32_16x16x32_bf16 v[52:55], v[198:201], v[162:165], v[52:55]
	v_mfma_f32_16x16x32_bf16 v[48:51], v[220:223], v[162:165], v[48:51]
	v_mfma_f32_16x16x32_bf16 v[36:39], v[198:201], v[170:173], v[36:39]
	v_mfma_f32_16x16x32_bf16 v[32:35], v[220:223], v[170:173], v[32:35]
	v_mfma_f32_16x16x32_bf16 v[20:23], v[198:201], v[178:181], v[20:23]
	v_mfma_f32_16x16x32_bf16 v[16:19], v[220:223], v[178:181], v[16:19]
	v_mfma_f32_16x16x32_bf16 v[4:7], v[198:201], v[190:193], v[4:7]
	v_mfma_f32_16x16x32_bf16 v[0:3], v[220:223], v[190:193], v[0:3]
	s_setprio 0
	s_add_i32 s35, s35, 2
	s_add_u32 s2, s2, 0x100
	s_addc_u32 s3, s3, 0
	s_add_u32 s22, s22, 0x100
	s_addc_u32 s23, s23, 0
	s_cmp_gt_u32 s35, 13
	s_barrier
	s_cbranch_scc0 .LBB0_372
	v_and_b32_e32 v250, 1, v204
	v_and_b32_e32 v251, 2, v204
	v_and_b32_e32 v246, 3, v204
	v_mul_u32_u24_e32 v246, 0x3ffe, v246
	v_mov_b32_e32 v247, v189
	v_and_b32_e32 v230, 16, v204
	v_lshrrev_b32_e32 v231, 1, v230
	v_add_u32_e32 v230, v230, v231
	v_mov_b32_e32 v231, v189
	s_lshl_b32 s35, s9, 8
	s_add_i32 s35, s35, s29
	s_lshl_b32 s2, s8, 8
	s_or_b32 s2, s2, s30
	s_ashr_i32 s3, s35, 12
	s_and_b32 s36, s3, -2
	v_or_b32_e32 v138, s2, v132
	s_movk_i32 s3, 0x49f
	v_bitop3_b32 v146, s35, v211, v142 bitop3:0xc8
	v_cmp_lt_i32_e64 s[4:5], s3, v138
	s_and_saveexec_b64 s[6:7], s[4:5]
	s_xor_b64 s[6:7], exec, s[6:7]
	s_cbranch_execz .LBB0_376
	s_cmpk_gt_u32 s2, 0x51f
	s_cbranch_scc1 .LBB0_376
	v_add_u32_e32 v139, 0xfffffb60, v138
	v_lshrrev_b32_e32 v140, 6, v139
	v_add_u32_e32 v140, s36, v140
	v_ashrrev_i32_e32 v141, 31, v140
	v_lshlrev_b64 v[140:141], 20, v[140:141]
	v_lshlrev_b32_e32 v139, 14, v139
	v_lshl_add_u64 v[140:141], s[90:91], 0, v[140:141]
	v_and_b32_e32 v188, 0xb0000, v139
	v_lshl_add_u64 v[140:141], v[140:141], 0, v[188:189]
	v_lshlrev_b32_e32 v188, 1, v146
	v_lshl_add_u64 v[140:141], v[140:141], 0, v[188:189]
	s_movk_i32 s3, 0x4000
	v_cmp_ne_u32_e32 vcc, 0, v250
	s_nop 1
	v_cndmask_b32_e32 v240, v125, v124, vcc
	v_cndmask_b32_e32 v241, v127, v126, vcc
	s_nop 1
	v_mov_b32_dpp v242, v240 quad_perm:[1,0,3,2] row_mask:0xf bank_mask:0xf
	v_mov_b32_dpp v243, v241 quad_perm:[1,0,3,2] row_mask:0xf bank_mask:0xf
	s_nop 1
	v_cndmask_b32_e32 v124, v124, v242, vcc
	v_cndmask_b32_e32 v125, v242, v125, vcc
	v_cndmask_b32_e32 v126, v126, v243, vcc
	v_cndmask_b32_e32 v127, v243, v127, vcc
	v_cmp_ne_u32_e32 vcc, 0, v251
	s_nop 1
	v_cndmask_b32_e32 v240, v126, v124, vcc
	v_cndmask_b32_e32 v241, v127, v125, vcc
	s_nop 1
	v_mov_b32_dpp v242, v240 quad_perm:[2,3,0,1] row_mask:0xf bank_mask:0xf
	v_mov_b32_dpp v243, v241 quad_perm:[2,3,0,1] row_mask:0xf bank_mask:0xf
	s_nop 1
	v_cndmask_b32_e32 v124, v124, v242, vcc
	v_cndmask_b32_e32 v126, v242, v126, vcc
	v_cndmask_b32_e32 v125, v125, v243, vcc
	v_cndmask_b32_e32 v127, v243, v127, vcc
	v_cvt_pk_bf16_f32 v244, v124, v125
	v_cvt_pk_bf16_f32 v245, v126, v127
	v_lshl_add_u64 v[248:249], v[140:141], 0, v[246:247]
	global_store_dwordx2 v[248:249], v[244:245], off
	s_nop 1

.LBB0_378:
	s_or_b64 exec, exec, s[6:7]
	v_or_b32_e32 v124, 16, v138
	s_movk_i32 s3, 0x49f
	v_cmp_lt_i32_e64 s[10:11], s3, v124
	s_and_saveexec_b64 s[6:7], s[10:11]
	s_xor_b64 s[6:7], exec, s[6:7]
	s_cbranch_execz .LBB0_381
	s_cmpk_gt_u32 s2, 0x51f
	s_cbranch_scc1 .LBB0_381
	v_add_u32_e32 v126, 0xfffffb70, v138
	v_lshrrev_b32_e32 v124, 6, v126
	v_add_u32_e32 v124, s36, v124
	v_ashrrev_i32_e32 v125, 31, v124
	v_lshlrev_b64 v[124:125], 20, v[124:125]
	v_lshlrev_b32_e32 v126, 14, v126
	v_lshl_add_u64 v[124:125], s[90:91], 0, v[124:125]
	v_and_b32_e32 v188, 0xf0000, v126
	v_lshl_add_u64 v[124:125], v[124:125], 0, v[188:189]
	v_lshlrev_b32_e32 v188, 1, v146
	v_lshl_add_u64 v[124:125], v[124:125], 0, v[188:189]
	v_cmp_ne_u32_e32 vcc, 0, v250
	s_nop 1
	v_cndmask_b32_e32 v240, v121, v120, vcc
	v_cndmask_b32_e32 v241, v123, v122, vcc
	s_nop 1
	v_mov_b32_dpp v242, v240 quad_perm:[1,0,3,2] row_mask:0xf bank_mask:0xf
	v_mov_b32_dpp v243, v241 quad_perm:[1,0,3,2] row_mask:0xf bank_mask:0xf
	s_nop 1
	v_cndmask_b32_e32 v120, v120, v242, vcc
	v_cndmask_b32_e32 v121, v242, v121, vcc
	v_cndmask_b32_e32 v122, v122, v243, vcc
	v_cndmask_b32_e32 v123, v243, v123, vcc
	v_cmp_ne_u32_e32 vcc, 0, v251
	s_nop 1
	v_cndmask_b32_e32 v240, v122, v120, vcc
	v_cndmask_b32_e32 v241, v123, v121, vcc
	s_nop 1
	v_mov_b32_dpp v242, v240 quad_perm:[2,3,0,1] row_mask:0xf bank_mask:0xf
	v_mov_b32_dpp v243, v241 quad_perm:[2,3,0,1] row_mask:0xf bank_mask:0xf
	s_nop 1
	v_cndmask_b32_e32 v120, v120, v242, vcc
	v_cndmask_b32_e32 v122, v242, v122, vcc
	v_cndmask_b32_e32 v121, v121, v243, vcc
	v_cndmask_b32_e32 v123, v243, v123, vcc
	v_cvt_pk_bf16_f32 v244, v120, v121
	v_cvt_pk_bf16_f32 v245, v122, v123
	v_lshl_add_u64 v[248:249], v[124:125], 0, v[246:247]
	global_store_dwordx2 v[248:249], v[244:245], off
	s_nop 1

.LBB0_383:
	s_or_b64 exec, exec, s[6:7]
	s_or_b32 s13, s2, 0x80
	v_or_b32_e32 v120, s13, v132
	v_cmp_lt_i32_e64 s[6:7], s3, v120
	s_and_saveexec_b64 s[8:9], s[6:7]
	s_xor_b64 s[8:9], exec, s[8:9]
	s_cbranch_execz .LBB0_386
	s_cmpk_gt_u32 s13, 0x51f
	s_cbranch_scc1 .LBB0_386
	v_add_u32_e32 v121, 0xfffffb60, v120
	v_lshrrev_b32_e32 v122, 6, v121
	v_add_u32_e32 v122, s36, v122
	v_ashrrev_i32_e32 v123, 31, v122
	v_lshlrev_b64 v[122:123], 20, v[122:123]
	v_lshlrev_b32_e32 v121, 14, v121
	v_lshl_add_u64 v[122:123], s[90:91], 0, v[122:123]
	v_and_b32_e32 v188, 0xfc000, v121
	v_lshl_add_u64 v[122:123], v[122:123], 0, v[188:189]
	v_lshlrev_b32_e32 v188, 1, v146
	v_lshl_add_u64 v[122:123], v[122:123], 0, v[188:189]
	v_cmp_ne_u32_e32 vcc, 0, v250
	s_nop 1
	v_cndmask_b32_e32 v240, v117, v116, vcc
	v_cndmask_b32_e32 v241, v119, v118, vcc
	s_nop 1
	v_mov_b32_dpp v242, v240 quad_perm:[1,0,3,2] row_mask:0xf bank_mask:0xf
	v_mov_b32_dpp v243, v241 quad_perm:[1,0,3,2] row_mask:0xf bank_mask:0xf
	s_nop 1
	v_cndmask_b32_e32 v116, v116, v242, vcc
	v_cndmask_b32_e32 v117, v242, v117, vcc
	v_cndmask_b32_e32 v118, v118, v243, vcc
	v_cndmask_b32_e32 v119, v243, v119, vcc
	v_cmp_ne_u32_e32 vcc, 0, v251
	s_nop 1
	v_cndmask_b32_e32 v240, v118, v116, vcc
	v_cndmask_b32_e32 v241, v119, v117, vcc
	s_nop 1
	v_mov_b32_dpp v242, v240 quad_perm:[2,3,0,1] row_mask:0xf bank_mask:0xf
	v_mov_b32_dpp v243, v241 quad_perm:[2,3,0,1] row_mask:0xf bank_mask:0xf
	s_nop 1
	v_cndmask_b32_e32 v116, v116, v242, vcc
	v_cndmask_b32_e32 v118, v242, v118, vcc
	v_cndmask_b32_e32 v117, v117, v243, vcc
	v_cndmask_b32_e32 v119, v243, v119, vcc
	v_cvt_pk_bf16_f32 v244, v116, v117
	v_cvt_pk_bf16_f32 v245, v118, v119
	v_lshl_add_u64 v[248:249], v[122:123], 0, v[246:247]
	global_store_dwordx2 v[248:249], v[244:245], off
	s_nop 1

.LBB0_388:
	s_or_b64 exec, exec, s[8:9]
	s_or_b32 s15, s2, 0x90
	v_or_b32_e32 v116, s15, v132
	s_movk_i32 s3, 0x49f
	v_cmp_lt_i32_e64 s[8:9], s3, v116
	s_and_saveexec_b64 s[22:23], s[8:9]
	s_xor_b64 s[22:23], exec, s[22:23]
	s_cbranch_execz .LBB0_391
	s_cmpk_gt_u32 s15, 0x51f
	s_cbranch_scc1 .LBB0_391
	v_add_u32_e32 v117, 0xfffffb60, v116
	v_lshrrev_b32_e32 v118, 6, v117
	v_add_u32_e32 v118, s36, v118
	v_ashrrev_i32_e32 v119, 31, v118
	v_lshlrev_b64 v[118:119], 20, v[118:119]
	v_lshlrev_b32_e32 v117, 14, v117
	v_lshl_add_u64 v[118:119], s[90:91], 0, v[118:119]
	v_and_b32_e32 v188, 0xfc000, v117
	v_lshl_add_u64 v[118:119], v[118:119], 0, v[188:189]
	v_lshlrev_b32_e32 v188, 1, v146
	v_lshl_add_u64 v[118:119], v[118:119], 0, v[188:189]
	v_cmp_ne_u32_e32 vcc, 0, v250
	s_nop 1
	v_cndmask_b32_e32 v240, v113, v112, vcc
	v_cndmask_b32_e32 v241, v115, v114, vcc
	s_nop 1
	v_mov_b32_dpp v242, v240 quad_perm:[1,0,3,2] row_mask:0xf bank_mask:0xf
	v_mov_b32_dpp v243, v241 quad_perm:[1,0,3,2] row_mask:0xf bank_mask:0xf
	s_nop 1
	v_cndmask_b32_e32 v112, v112, v242, vcc
	v_cndmask_b32_e32 v113, v242, v113, vcc
	v_cndmask_b32_e32 v114, v114, v243, vcc
	v_cndmask_b32_e32 v115, v243, v115, vcc
	v_cmp_ne_u32_e32 vcc, 0, v251
	s_nop 1
	v_cndmask_b32_e32 v240, v114, v112, vcc
	v_cndmask_b32_e32 v241, v115, v113, vcc
	s_nop 1
	v_mov_b32_dpp v242, v240 quad_perm:[2,3,0,1] row_mask:0xf bank_mask:0xf
	v_mov_b32_dpp v243, v241 quad_perm:[2,3,0,1] row_mask:0xf bank_mask:0xf
	s_nop 1
	v_cndmask_b32_e32 v112, v112, v242, vcc
	v_cndmask_b32_e32 v114, v242, v114, vcc
	v_cndmask_b32_e32 v113, v113, v243, vcc
	v_cndmask_b32_e32 v115, v243, v115, vcc
	v_cvt_pk_bf16_f32 v244, v112, v113
	v_cvt_pk_bf16_f32 v245, v114, v115
	v_lshl_add_u64 v[248:249], v[118:119], 0, v[246:247]
	global_store_dwordx2 v[248:249], v[244:245], off
	s_nop 1

.LBB0_393:
	s_or_b64 exec, exec, s[22:23]
	s_movk_i32 s3, 0x1fdf
	v_bitop3_b32 v114, v145, s3, 16 bitop3:0xc8
	s_and_saveexec_b64 s[22:23], s[4:5]
	s_xor_b64 s[22:23], exec, s[22:23]
	s_cbranch_execz .LBB0_396
	s_cmpk_gt_u32 s2, 0x51f
	s_cbranch_scc1 .LBB0_396
	v_add_u32_e32 v115, 0xfffffb60, v138
	v_lshrrev_b32_e32 v112, 6, v115
	v_add_u32_e32 v112, s36, v112
	v_ashrrev_i32_e32 v113, 31, v112
	v_lshlrev_b64 v[112:113], 20, v[112:113]
	v_lshlrev_b32_e32 v115, 14, v115
	v_lshl_add_u64 v[112:113], s[90:91], 0, v[112:113]
	v_and_b32_e32 v188, 0xb0000, v115
	v_lshl_add_u64 v[112:113], v[112:113], 0, v[188:189]
	v_lshlrev_b32_e32 v188, 1, v114
	v_lshl_add_u64 v[112:113], v[112:113], 0, v[188:189]
	v_cmp_ne_u32_e32 vcc, 0, v250
	s_nop 1
	v_cndmask_b32_e32 v240, v109, v108, vcc
	v_cndmask_b32_e32 v241, v111, v110, vcc
	s_nop 1
	v_mov_b32_dpp v242, v240 quad_perm:[1,0,3,2] row_mask:0xf bank_mask:0xf
	v_mov_b32_dpp v243, v241 quad_perm:[1,0,3,2] row_mask:0xf bank_mask:0xf
	s_nop 1
	v_cndmask_b32_e32 v108, v108, v242, vcc
	v_cndmask_b32_e32 v109, v242, v109, vcc
	v_cndmask_b32_e32 v110, v110, v243, vcc
	v_cndmask_b32_e32 v111, v243, v111, vcc
	v_cmp_ne_u32_e32 vcc, 0, v251
	s_nop 1
	v_cndmask_b32_e32 v240, v110, v108, vcc
	v_cndmask_b32_e32 v241, v111, v109, vcc
	s_nop 1
	v_mov_b32_dpp v242, v240 quad_perm:[2,3,0,1] row_mask:0xf bank_mask:0xf
	v_mov_b32_dpp v243, v241 quad_perm:[2,3,0,1] row_mask:0xf bank_mask:0xf
	s_nop 1
	v_cndmask_b32_e32 v108, v108, v242, vcc
	v_cndmask_b32_e32 v110, v242, v110, vcc
	v_cndmask_b32_e32 v109, v109, v243, vcc
	v_cndmask_b32_e32 v111, v243, v111, vcc
	v_cvt_pk_bf16_f32 v244, v108, v109
	v_cvt_pk_bf16_f32 v245, v110, v111
	v_lshl_add_u64 v[248:249], v[112:113], 0, v[246:247]
	global_store_dwordx2 v[248:249], v[244:245], off
	s_nop 1

.LBB0_398:
	s_or_b64 exec, exec, s[22:23]
	s_and_saveexec_b64 s[22:23], s[10:11]
	s_xor_b64 s[22:23], exec, s[22:23]
	s_cbranch_execz .LBB0_401
	s_cmpk_gt_u32 s2, 0x51f
	s_cbranch_scc1 .LBB0_401
	v_add_u32_e32 v110, 0xfffffb70, v138
	v_lshrrev_b32_e32 v108, 6, v110
	v_add_u32_e32 v108, s36, v108
	v_ashrrev_i32_e32 v109, 31, v108
	v_lshlrev_b64 v[108:109], 20, v[108:109]
	v_lshlrev_b32_e32 v110, 14, v110
	v_lshl_add_u64 v[108:109], s[90:91], 0, v[108:109]
	v_and_b32_e32 v188, 0xf0000, v110
	v_lshl_add_u64 v[108:109], v[108:109], 0, v[188:189]
	v_lshlrev_b32_e32 v188, 1, v114
	v_lshl_add_u64 v[108:109], v[108:109], 0, v[188:189]
	v_cmp_ne_u32_e32 vcc, 0, v250
	s_nop 1
	v_cndmask_b32_e32 v240, v105, v104, vcc
	v_cndmask_b32_e32 v241, v107, v106, vcc
	s_nop 1
	v_mov_b32_dpp v242, v240 quad_perm:[1,0,3,2] row_mask:0xf bank_mask:0xf
	v_mov_b32_dpp v243, v241 quad_perm:[1,0,3,2] row_mask:0xf bank_mask:0xf
	s_nop 1
	v_cndmask_b32_e32 v104, v104, v242, vcc
	v_cndmask_b32_e32 v105, v242, v105, vcc
	v_cndmask_b32_e32 v106, v106, v243, vcc
	v_cndmask_b32_e32 v107, v243, v107, vcc
	v_cmp_ne_u32_e32 vcc, 0, v251
	s_nop 1
	v_cndmask_b32_e32 v240, v106, v104, vcc
	v_cndmask_b32_e32 v241, v107, v105, vcc
	s_nop 1
	v_mov_b32_dpp v242, v240 quad_perm:[2,3,0,1] row_mask:0xf bank_mask:0xf
	v_mov_b32_dpp v243, v241 quad_perm:[2,3,0,1] row_mask:0xf bank_mask:0xf
	s_nop 1
	v_cndmask_b32_e32 v104, v104, v242, vcc
	v_cndmask_b32_e32 v106, v242, v106, vcc
	v_cndmask_b32_e32 v105, v105, v243, vcc
	v_cndmask_b32_e32 v107, v243, v107, vcc
	v_cvt_pk_bf16_f32 v244, v104, v105
	v_cvt_pk_bf16_f32 v245, v106, v107
	v_lshl_add_u64 v[248:249], v[108:109], 0, v[246:247]
	global_store_dwordx2 v[248:249], v[244:245], off
	s_nop 1

.LBB0_403:
	s_or_b64 exec, exec, s[22:23]
	s_and_saveexec_b64 s[22:23], s[6:7]
	s_xor_b64 s[22:23], exec, s[22:23]
	s_cbranch_execz .LBB0_406
	s_cmpk_gt_u32 s13, 0x51f
	s_cbranch_scc1 .LBB0_406
	v_add_u32_e32 v106, 0xfffffb60, v120
	v_lshrrev_b32_e32 v104, 6, v106
	v_add_u32_e32 v104, s36, v104
	v_ashrrev_i32_e32 v105, 31, v104
	v_lshlrev_b64 v[104:105], 20, v[104:105]
	v_lshlrev_b32_e32 v106, 14, v106
	v_lshl_add_u64 v[104:105], s[90:91], 0, v[104:105]
	v_and_b32_e32 v188, 0xfc000, v106
	v_lshl_add_u64 v[104:105], v[104:105], 0, v[188:189]
	v_lshlrev_b32_e32 v188, 1, v114
	v_lshl_add_u64 v[104:105], v[104:105], 0, v[188:189]
	v_cmp_ne_u32_e32 vcc, 0, v250
	s_nop 1
	v_cndmask_b32_e32 v240, v101, v100, vcc
	v_cndmask_b32_e32 v241, v103, v102, vcc
	s_nop 1
	v_mov_b32_dpp v242, v240 quad_perm:[1,0,3,2] row_mask:0xf bank_mask:0xf
	v_mov_b32_dpp v243, v241 quad_perm:[1,0,3,2] row_mask:0xf bank_mask:0xf
	s_nop 1
	v_cndmask_b32_e32 v100, v100, v242, vcc
	v_cndmask_b32_e32 v101, v242, v101, vcc
	v_cndmask_b32_e32 v102, v102, v243, vcc
	v_cndmask_b32_e32 v103, v243, v103, vcc
	v_cmp_ne_u32_e32 vcc, 0, v251
	s_nop 1
	v_cndmask_b32_e32 v240, v102, v100, vcc
	v_cndmask_b32_e32 v241, v103, v101, vcc
	s_nop 1
	v_mov_b32_dpp v242, v240 quad_perm:[2,3,0,1] row_mask:0xf bank_mask:0xf
	v_mov_b32_dpp v243, v241 quad_perm:[2,3,0,1] row_mask:0xf bank_mask:0xf
	s_nop 1
	v_cndmask_b32_e32 v100, v100, v242, vcc
	v_cndmask_b32_e32 v102, v242, v102, vcc
	v_cndmask_b32_e32 v101, v101, v243, vcc
	v_cndmask_b32_e32 v103, v243, v103, vcc
	v_cvt_pk_bf16_f32 v244, v100, v101
	v_cvt_pk_bf16_f32 v245, v102, v103
	v_lshl_add_u64 v[248:249], v[104:105], 0, v[246:247]
	global_store_dwordx2 v[248:249], v[244:245], off
	s_nop 1

.LBB0_408:
	s_or_b64 exec, exec, s[22:23]
	s_and_saveexec_b64 s[22:23], s[8:9]
	s_xor_b64 s[22:23], exec, s[22:23]
	s_cbranch_execz .LBB0_411
	s_cmpk_gt_u32 s15, 0x51f
	s_cbranch_scc1 .LBB0_411
	v_add_u32_e32 v102, 0xfffffb60, v116
	v_lshrrev_b32_e32 v100, 6, v102
	v_add_u32_e32 v100, s36, v100
	v_ashrrev_i32_e32 v101, 31, v100
	v_lshlrev_b64 v[100:101], 20, v[100:101]
	v_lshlrev_b32_e32 v102, 14, v102
	v_lshl_add_u64 v[100:101], s[90:91], 0, v[100:101]
	v_and_b32_e32 v188, 0xfc000, v102
	v_lshl_add_u64 v[100:101], v[100:101], 0, v[188:189]
	v_lshlrev_b32_e32 v188, 1, v114
	v_lshl_add_u64 v[100:101], v[100:101], 0, v[188:189]
	v_cmp_ne_u32_e32 vcc, 0, v250
	s_nop 1
	v_cndmask_b32_e32 v240, v97, v96, vcc
	v_cndmask_b32_e32 v241, v99, v98, vcc
	s_nop 1
	v_mov_b32_dpp v242, v240 quad_perm:[1,0,3,2] row_mask:0xf bank_mask:0xf
	v_mov_b32_dpp v243, v241 quad_perm:[1,0,3,2] row_mask:0xf bank_mask:0xf
	s_nop 1
	v_cndmask_b32_e32 v96, v96, v242, vcc
	v_cndmask_b32_e32 v97, v242, v97, vcc
	v_cndmask_b32_e32 v98, v98, v243, vcc
	v_cndmask_b32_e32 v99, v243, v99, vcc
	v_cmp_ne_u32_e32 vcc, 0, v251
	s_nop 1
	v_cndmask_b32_e32 v240, v98, v96, vcc
	v_cndmask_b32_e32 v241, v99, v97, vcc
	s_nop 1
	v_mov_b32_dpp v242, v240 quad_perm:[2,3,0,1] row_mask:0xf bank_mask:0xf
	v_mov_b32_dpp v243, v241 quad_perm:[2,3,0,1] row_mask:0xf bank_mask:0xf
	s_nop 1
	v_cndmask_b32_e32 v96, v96, v242, vcc
	v_cndmask_b32_e32 v98, v242, v98, vcc
	v_cndmask_b32_e32 v97, v97, v243, vcc
	v_cndmask_b32_e32 v99, v243, v99, vcc
	v_cvt_pk_bf16_f32 v244, v96, v97
	v_cvt_pk_bf16_f32 v245, v98, v99
	v_lshl_add_u64 v[248:249], v[100:101], 0, v[246:247]
	global_store_dwordx2 v[248:249], v[244:245], off
	s_nop 1

.LBB0_413:
	s_or_b64 exec, exec, s[22:23]
	s_movk_i32 s3, 0x1fef
	v_bitop3_b32 v98, v145, s3, 32 bitop3:0xc8
	s_and_saveexec_b64 s[22:23], s[4:5]
	s_xor_b64 s[22:23], exec, s[22:23]
	s_cbranch_execz .LBB0_416
	s_cmpk_gt_u32 s2, 0x51f
	s_cbranch_scc1 .LBB0_416
	v_add_u32_e32 v99, 0xfffffb60, v138
	v_lshrrev_b32_e32 v96, 6, v99
	v_add_u32_e32 v96, s36, v96
	v_ashrrev_i32_e32 v97, 31, v96
	v_lshlrev_b64 v[96:97], 20, v[96:97]
	v_lshlrev_b32_e32 v99, 14, v99
	v_lshl_add_u64 v[96:97], s[90:91], 0, v[96:97]
	v_and_b32_e32 v188, 0xb0000, v99
	v_lshl_add_u64 v[96:97], v[96:97], 0, v[188:189]
	v_lshlrev_b32_e32 v188, 1, v98
	v_lshl_add_u64 v[96:97], v[96:97], 0, v[188:189]
	v_cmp_ne_u32_e32 vcc, 0, v250
	s_nop 1
	v_cndmask_b32_e32 v240, v93, v92, vcc
	v_cndmask_b32_e32 v241, v95, v94, vcc
	s_nop 1
	v_mov_b32_dpp v242, v240 quad_perm:[1,0,3,2] row_mask:0xf bank_mask:0xf
	v_mov_b32_dpp v243, v241 quad_perm:[1,0,3,2] row_mask:0xf bank_mask:0xf
	s_nop 1
	v_cndmask_b32_e32 v92, v92, v242, vcc
	v_cndmask_b32_e32 v93, v242, v93, vcc
	v_cndmask_b32_e32 v94, v94, v243, vcc
	v_cndmask_b32_e32 v95, v243, v95, vcc
	v_cmp_ne_u32_e32 vcc, 0, v251
	s_nop 1
	v_cndmask_b32_e32 v240, v94, v92, vcc
	v_cndmask_b32_e32 v241, v95, v93, vcc
	s_nop 1
	v_mov_b32_dpp v242, v240 quad_perm:[2,3,0,1] row_mask:0xf bank_mask:0xf
	v_mov_b32_dpp v243, v241 quad_perm:[2,3,0,1] row_mask:0xf bank_mask:0xf
	s_nop 1
	v_cndmask_b32_e32 v92, v92, v242, vcc
	v_cndmask_b32_e32 v94, v242, v94, vcc
	v_cndmask_b32_e32 v93, v93, v243, vcc
	v_cndmask_b32_e32 v95, v243, v95, vcc
	v_cvt_pk_bf16_f32 v244, v92, v93
	v_cvt_pk_bf16_f32 v245, v94, v95
	v_lshl_add_u64 v[248:249], v[96:97], 0, v[246:247]
	global_store_dwordx2 v[248:249], v[244:245], off
	s_nop 1

.LBB0_418:
	s_or_b64 exec, exec, s[22:23]
	s_and_saveexec_b64 s[22:23], s[10:11]
	s_xor_b64 s[22:23], exec, s[22:23]
	s_cbranch_execz .LBB0_421
	s_cmpk_gt_u32 s2, 0x51f
	s_cbranch_scc1 .LBB0_421
	v_add_u32_e32 v94, 0xfffffb70, v138
	v_lshrrev_b32_e32 v92, 6, v94
	v_add_u32_e32 v92, s36, v92
	v_ashrrev_i32_e32 v93, 31, v92
	v_lshlrev_b64 v[92:93], 20, v[92:93]
	v_lshlrev_b32_e32 v94, 14, v94
	v_lshl_add_u64 v[92:93], s[90:91], 0, v[92:93]
	v_and_b32_e32 v188, 0xf0000, v94
	v_lshl_add_u64 v[92:93], v[92:93], 0, v[188:189]
	v_lshlrev_b32_e32 v188, 1, v98
	v_lshl_add_u64 v[92:93], v[92:93], 0, v[188:189]
	v_cmp_ne_u32_e32 vcc, 0, v250
	s_nop 1
	v_cndmask_b32_e32 v240, v89, v88, vcc
	v_cndmask_b32_e32 v241, v91, v90, vcc
	s_nop 1
	v_mov_b32_dpp v242, v240 quad_perm:[1,0,3,2] row_mask:0xf bank_mask:0xf
	v_mov_b32_dpp v243, v241 quad_perm:[1,0,3,2] row_mask:0xf bank_mask:0xf
	s_nop 1
	v_cndmask_b32_e32 v88, v88, v242, vcc
	v_cndmask_b32_e32 v89, v242, v89, vcc
	v_cndmask_b32_e32 v90, v90, v243, vcc
	v_cndmask_b32_e32 v91, v243, v91, vcc
	v_cmp_ne_u32_e32 vcc, 0, v251
	s_nop 1
	v_cndmask_b32_e32 v240, v90, v88, vcc
	v_cndmask_b32_e32 v241, v91, v89, vcc
	s_nop 1
	v_mov_b32_dpp v242, v240 quad_perm:[2,3,0,1] row_mask:0xf bank_mask:0xf
	v_mov_b32_dpp v243, v241 quad_perm:[2,3,0,1] row_mask:0xf bank_mask:0xf
	s_nop 1
	v_cndmask_b32_e32 v88, v88, v242, vcc
	v_cndmask_b32_e32 v90, v242, v90, vcc
	v_cndmask_b32_e32 v89, v89, v243, vcc
	v_cndmask_b32_e32 v91, v243, v91, vcc
	v_cvt_pk_bf16_f32 v244, v88, v89
	v_cvt_pk_bf16_f32 v245, v90, v91
	v_lshl_add_u64 v[248:249], v[92:93], 0, v[246:247]
	global_store_dwordx2 v[248:249], v[244:245], off
	s_nop 1

.LBB0_423:
	s_or_b64 exec, exec, s[22:23]
	s_and_saveexec_b64 s[22:23], s[6:7]
	s_xor_b64 s[22:23], exec, s[22:23]
	s_cbranch_execz .LBB0_426
	s_cmpk_gt_u32 s13, 0x51f
	s_cbranch_scc1 .LBB0_426
	v_add_u32_e32 v90, 0xfffffb60, v120
	v_lshrrev_b32_e32 v88, 6, v90
	v_add_u32_e32 v88, s36, v88
	v_ashrrev_i32_e32 v89, 31, v88
	v_lshlrev_b64 v[88:89], 20, v[88:89]
	v_lshlrev_b32_e32 v90, 14, v90
	v_lshl_add_u64 v[88:89], s[90:91], 0, v[88:89]
	v_and_b32_e32 v188, 0xfc000, v90
	v_lshl_add_u64 v[88:89], v[88:89], 0, v[188:189]
	v_lshlrev_b32_e32 v188, 1, v98
	v_lshl_add_u64 v[88:89], v[88:89], 0, v[188:189]
	v_cmp_ne_u32_e32 vcc, 0, v250
	s_nop 1
	v_cndmask_b32_e32 v240, v85, v84, vcc
	v_cndmask_b32_e32 v241, v87, v86, vcc
	s_nop 1
	v_mov_b32_dpp v242, v240 quad_perm:[1,0,3,2] row_mask:0xf bank_mask:0xf
	v_mov_b32_dpp v243, v241 quad_perm:[1,0,3,2] row_mask:0xf bank_mask:0xf
	s_nop 1
	v_cndmask_b32_e32 v84, v84, v242, vcc
	v_cndmask_b32_e32 v85, v242, v85, vcc
	v_cndmask_b32_e32 v86, v86, v243, vcc
	v_cndmask_b32_e32 v87, v243, v87, vcc
	v_cmp_ne_u32_e32 vcc, 0, v251
	s_nop 1
	v_cndmask_b32_e32 v240, v86, v84, vcc
	v_cndmask_b32_e32 v241, v87, v85, vcc
	s_nop 1
	v_mov_b32_dpp v242, v240 quad_perm:[2,3,0,1] row_mask:0xf bank_mask:0xf
	v_mov_b32_dpp v243, v241 quad_perm:[2,3,0,1] row_mask:0xf bank_mask:0xf
	s_nop 1
	v_cndmask_b32_e32 v84, v84, v242, vcc
	v_cndmask_b32_e32 v86, v242, v86, vcc
	v_cndmask_b32_e32 v85, v85, v243, vcc
	v_cndmask_b32_e32 v87, v243, v87, vcc
	v_cvt_pk_bf16_f32 v244, v84, v85
	v_cvt_pk_bf16_f32 v245, v86, v87
	v_lshl_add_u64 v[248:249], v[88:89], 0, v[246:247]
	global_store_dwordx2 v[248:249], v[244:245], off
	s_nop 1

.LBB0_428:
	s_or_b64 exec, exec, s[22:23]
	s_and_saveexec_b64 s[22:23], s[8:9]
	s_xor_b64 s[22:23], exec, s[22:23]
	s_cbranch_execz .LBB0_431
	s_cmpk_gt_u32 s15, 0x51f
	s_cbranch_scc1 .LBB0_431
	v_add_u32_e32 v86, 0xfffffb60, v116
	v_lshrrev_b32_e32 v84, 6, v86
	v_add_u32_e32 v84, s36, v84
	v_ashrrev_i32_e32 v85, 31, v84
	v_lshlrev_b64 v[84:85], 20, v[84:85]
	v_lshlrev_b32_e32 v86, 14, v86
	v_lshl_add_u64 v[84:85], s[90:91], 0, v[84:85]
	v_and_b32_e32 v188, 0xfc000, v86
	v_lshl_add_u64 v[84:85], v[84:85], 0, v[188:189]
	v_lshlrev_b32_e32 v188, 1, v98
	v_lshl_add_u64 v[84:85], v[84:85], 0, v[188:189]
	v_cmp_ne_u32_e32 vcc, 0, v250
	s_nop 1
	v_cndmask_b32_e32 v240, v81, v80, vcc
	v_cndmask_b32_e32 v241, v83, v82, vcc
	s_nop 1
	v_mov_b32_dpp v242, v240 quad_perm:[1,0,3,2] row_mask:0xf bank_mask:0xf
	v_mov_b32_dpp v243, v241 quad_perm:[1,0,3,2] row_mask:0xf bank_mask:0xf
	s_nop 1
	v_cndmask_b32_e32 v80, v80, v242, vcc
	v_cndmask_b32_e32 v81, v242, v81, vcc
	v_cndmask_b32_e32 v82, v82, v243, vcc
	v_cndmask_b32_e32 v83, v243, v83, vcc
	v_cmp_ne_u32_e32 vcc, 0, v251
	s_nop 1
	v_cndmask_b32_e32 v240, v82, v80, vcc
	v_cndmask_b32_e32 v241, v83, v81, vcc
	s_nop 1
	v_mov_b32_dpp v242, v240 quad_perm:[2,3,0,1] row_mask:0xf bank_mask:0xf
	v_mov_b32_dpp v243, v241 quad_perm:[2,3,0,1] row_mask:0xf bank_mask:0xf
	s_nop 1
	v_cndmask_b32_e32 v80, v80, v242, vcc
	v_cndmask_b32_e32 v82, v242, v82, vcc
	v_cndmask_b32_e32 v81, v81, v243, vcc
	v_cndmask_b32_e32 v83, v243, v83, vcc
	v_cvt_pk_bf16_f32 v244, v80, v81
	v_cvt_pk_bf16_f32 v245, v82, v83
	v_lshl_add_u64 v[248:249], v[84:85], 0, v[246:247]
	global_store_dwordx2 v[248:249], v[244:245], off
	s_nop 1

.LBB0_433:
	s_or_b64 exec, exec, s[22:23]
	s_movk_i32 s3, 0x1fff
	v_bitop3_b32 v82, v145, s3, 48 bitop3:0xc8
	s_and_saveexec_b64 s[22:23], s[4:5]
	s_xor_b64 s[22:23], exec, s[22:23]
	s_cbranch_execz .LBB0_436
	s_cmpk_gt_u32 s2, 0x51f
	s_cbranch_scc1 .LBB0_436
	v_add_u32_e32 v83, 0xfffffb60, v138
	v_lshrrev_b32_e32 v80, 6, v83
	v_add_u32_e32 v80, s36, v80
	v_ashrrev_i32_e32 v81, 31, v80
	v_lshlrev_b64 v[80:81], 20, v[80:81]
	v_lshlrev_b32_e32 v83, 14, v83
	v_lshl_add_u64 v[80:81], s[90:91], 0, v[80:81]
	v_and_b32_e32 v188, 0xb0000, v83
	v_lshl_add_u64 v[80:81], v[80:81], 0, v[188:189]
	v_lshlrev_b32_e32 v188, 1, v82
	v_lshl_add_u64 v[80:81], v[80:81], 0, v[188:189]
	v_cmp_ne_u32_e32 vcc, 0, v250
	s_nop 1
	v_cndmask_b32_e32 v240, v77, v76, vcc
	v_cndmask_b32_e32 v241, v79, v78, vcc
	s_nop 1
	v_mov_b32_dpp v242, v240 quad_perm:[1,0,3,2] row_mask:0xf bank_mask:0xf
	v_mov_b32_dpp v243, v241 quad_perm:[1,0,3,2] row_mask:0xf bank_mask:0xf
	s_nop 1
	v_cndmask_b32_e32 v76, v76, v242, vcc
	v_cndmask_b32_e32 v77, v242, v77, vcc
	v_cndmask_b32_e32 v78, v78, v243, vcc
	v_cndmask_b32_e32 v79, v243, v79, vcc
	v_cmp_ne_u32_e32 vcc, 0, v251
	s_nop 1
	v_cndmask_b32_e32 v240, v78, v76, vcc
	v_cndmask_b32_e32 v241, v79, v77, vcc
	s_nop 1
	v_mov_b32_dpp v242, v240 quad_perm:[2,3,0,1] row_mask:0xf bank_mask:0xf
	v_mov_b32_dpp v243, v241 quad_perm:[2,3,0,1] row_mask:0xf bank_mask:0xf
	s_nop 1
	v_cndmask_b32_e32 v76, v76, v242, vcc
	v_cndmask_b32_e32 v78, v242, v78, vcc
	v_cndmask_b32_e32 v77, v77, v243, vcc
	v_cndmask_b32_e32 v79, v243, v79, vcc
	v_cvt_pk_bf16_f32 v244, v76, v77
	v_cvt_pk_bf16_f32 v245, v78, v79
	v_lshl_add_u64 v[248:249], v[80:81], 0, v[246:247]
	global_store_dwordx2 v[248:249], v[244:245], off
	s_nop 1

.LBB0_438:
	s_or_b64 exec, exec, s[22:23]
	s_and_saveexec_b64 s[22:23], s[10:11]
	s_xor_b64 s[22:23], exec, s[22:23]
	s_cbranch_execz .LBB0_441
	s_cmpk_gt_u32 s2, 0x51f
	s_cbranch_scc1 .LBB0_441
	v_add_u32_e32 v78, 0xfffffb70, v138
	v_lshrrev_b32_e32 v76, 6, v78
	v_add_u32_e32 v76, s36, v76
	v_ashrrev_i32_e32 v77, 31, v76
	v_lshlrev_b64 v[76:77], 20, v[76:77]
	v_lshlrev_b32_e32 v78, 14, v78
	v_lshl_add_u64 v[76:77], s[90:91], 0, v[76:77]
	v_and_b32_e32 v188, 0xf0000, v78
	v_lshl_add_u64 v[76:77], v[76:77], 0, v[188:189]
	v_lshlrev_b32_e32 v188, 1, v82
	v_lshl_add_u64 v[76:77], v[76:77], 0, v[188:189]
	v_cmp_ne_u32_e32 vcc, 0, v250
	s_nop 1
	v_cndmask_b32_e32 v240, v73, v72, vcc
	v_cndmask_b32_e32 v241, v75, v74, vcc
	s_nop 1
	v_mov_b32_dpp v242, v240 quad_perm:[1,0,3,2] row_mask:0xf bank_mask:0xf
	v_mov_b32_dpp v243, v241 quad_perm:[1,0,3,2] row_mask:0xf bank_mask:0xf
	s_nop 1
	v_cndmask_b32_e32 v72, v72, v242, vcc
	v_cndmask_b32_e32 v73, v242, v73, vcc
	v_cndmask_b32_e32 v74, v74, v243, vcc
	v_cndmask_b32_e32 v75, v243, v75, vcc
	v_cmp_ne_u32_e32 vcc, 0, v251
	s_nop 1
	v_cndmask_b32_e32 v240, v74, v72, vcc
	v_cndmask_b32_e32 v241, v75, v73, vcc
	s_nop 1
	v_mov_b32_dpp v242, v240 quad_perm:[2,3,0,1] row_mask:0xf bank_mask:0xf
	v_mov_b32_dpp v243, v241 quad_perm:[2,3,0,1] row_mask:0xf bank_mask:0xf
	s_nop 1
	v_cndmask_b32_e32 v72, v72, v242, vcc
	v_cndmask_b32_e32 v74, v242, v74, vcc
	v_cndmask_b32_e32 v73, v73, v243, vcc
	v_cndmask_b32_e32 v75, v243, v75, vcc
	v_cvt_pk_bf16_f32 v244, v72, v73
	v_cvt_pk_bf16_f32 v245, v74, v75
	v_lshl_add_u64 v[248:249], v[76:77], 0, v[246:247]
	global_store_dwordx2 v[248:249], v[244:245], off
	s_nop 1

.LBB0_443:
	s_or_b64 exec, exec, s[22:23]
	s_and_saveexec_b64 s[22:23], s[6:7]
	s_xor_b64 s[22:23], exec, s[22:23]
	s_cbranch_execz .LBB0_446
	s_cmpk_gt_u32 s13, 0x51f
	s_cbranch_scc1 .LBB0_446
	v_add_u32_e32 v74, 0xfffffb60, v120
	v_lshrrev_b32_e32 v72, 6, v74
	v_add_u32_e32 v72, s36, v72
	v_ashrrev_i32_e32 v73, 31, v72
	v_lshlrev_b64 v[72:73], 20, v[72:73]
	v_lshlrev_b32_e32 v74, 14, v74
	v_lshl_add_u64 v[72:73], s[90:91], 0, v[72:73]
	v_and_b32_e32 v188, 0xfc000, v74
	v_lshl_add_u64 v[72:73], v[72:73], 0, v[188:189]
	v_lshlrev_b32_e32 v188, 1, v82
	v_lshl_add_u64 v[72:73], v[72:73], 0, v[188:189]
	v_cmp_ne_u32_e32 vcc, 0, v250
	s_nop 1
	v_cndmask_b32_e32 v240, v69, v68, vcc
	v_cndmask_b32_e32 v241, v71, v70, vcc
	s_nop 1
	v_mov_b32_dpp v242, v240 quad_perm:[1,0,3,2] row_mask:0xf bank_mask:0xf
	v_mov_b32_dpp v243, v241 quad_perm:[1,0,3,2] row_mask:0xf bank_mask:0xf
	s_nop 1
	v_cndmask_b32_e32 v68, v68, v242, vcc
	v_cndmask_b32_e32 v69, v242, v69, vcc
	v_cndmask_b32_e32 v70, v70, v243, vcc
	v_cndmask_b32_e32 v71, v243, v71, vcc
	v_cmp_ne_u32_e32 vcc, 0, v251
	s_nop 1
	v_cndmask_b32_e32 v240, v70, v68, vcc
	v_cndmask_b32_e32 v241, v71, v69, vcc
	s_nop 1
	v_mov_b32_dpp v242, v240 quad_perm:[2,3,0,1] row_mask:0xf bank_mask:0xf
	v_mov_b32_dpp v243, v241 quad_perm:[2,3,0,1] row_mask:0xf bank_mask:0xf
	s_nop 1
	v_cndmask_b32_e32 v68, v68, v242, vcc
	v_cndmask_b32_e32 v70, v242, v70, vcc
	v_cndmask_b32_e32 v69, v69, v243, vcc
	v_cndmask_b32_e32 v71, v243, v71, vcc
	v_cvt_pk_bf16_f32 v244, v68, v69
	v_cvt_pk_bf16_f32 v245, v70, v71
	v_lshl_add_u64 v[248:249], v[72:73], 0, v[246:247]
	global_store_dwordx2 v[248:249], v[244:245], off
	s_nop 1

.LBB0_448:
	s_or_b64 exec, exec, s[22:23]
	s_and_saveexec_b64 s[22:23], s[8:9]
	s_xor_b64 s[22:23], exec, s[22:23]
	s_cbranch_execz .LBB0_451
	s_cmpk_gt_u32 s15, 0x51f
	s_cbranch_scc1 .LBB0_451
	v_add_u32_e32 v70, 0xfffffb60, v116
	v_lshrrev_b32_e32 v68, 6, v70
	v_add_u32_e32 v68, s36, v68
	v_ashrrev_i32_e32 v69, 31, v68
	v_lshlrev_b64 v[68:69], 20, v[68:69]
	v_lshlrev_b32_e32 v70, 14, v70
	v_lshl_add_u64 v[68:69], s[90:91], 0, v[68:69]
	v_and_b32_e32 v188, 0xfc000, v70
	v_lshl_add_u64 v[68:69], v[68:69], 0, v[188:189]
	v_lshlrev_b32_e32 v188, 1, v82
	v_lshl_add_u64 v[68:69], v[68:69], 0, v[188:189]
	v_cmp_ne_u32_e32 vcc, 0, v250
	s_nop 1
	v_cndmask_b32_e32 v240, v65, v64, vcc
	v_cndmask_b32_e32 v241, v67, v66, vcc
	s_nop 1
	v_mov_b32_dpp v242, v240 quad_perm:[1,0,3,2] row_mask:0xf bank_mask:0xf
	v_mov_b32_dpp v243, v241 quad_perm:[1,0,3,2] row_mask:0xf bank_mask:0xf
	s_nop 1
	v_cndmask_b32_e32 v64, v64, v242, vcc
	v_cndmask_b32_e32 v65, v242, v65, vcc
	v_cndmask_b32_e32 v66, v66, v243, vcc
	v_cndmask_b32_e32 v67, v243, v67, vcc
	v_cmp_ne_u32_e32 vcc, 0, v251
	s_nop 1
	v_cndmask_b32_e32 v240, v66, v64, vcc
	v_cndmask_b32_e32 v241, v67, v65, vcc
	s_nop 1
	v_mov_b32_dpp v242, v240 quad_perm:[2,3,0,1] row_mask:0xf bank_mask:0xf
	v_mov_b32_dpp v243, v241 quad_perm:[2,3,0,1] row_mask:0xf bank_mask:0xf
	s_nop 1
	v_cndmask_b32_e32 v64, v64, v242, vcc
	v_cndmask_b32_e32 v66, v242, v66, vcc
	v_cndmask_b32_e32 v65, v65, v243, vcc
	v_cndmask_b32_e32 v67, v243, v67, vcc
	v_cvt_pk_bf16_f32 v244, v64, v65
	v_cvt_pk_bf16_f32 v245, v66, v67
	v_lshl_add_u64 v[248:249], v[68:69], 0, v[246:247]
	global_store_dwordx2 v[248:249], v[244:245], off
	s_nop 1

.LBB0_453:
	s_or_b64 exec, exec, s[22:23]
	s_add_i32 s3, s35, 0x80
	s_ashr_i32 s22, s3, 12
	s_and_b32 s35, s22, -2
	v_bitop3_b32 v67, s3, v211, v142 bitop3:0xc8
	s_and_saveexec_b64 s[22:23], s[4:5]
	s_xor_b64 s[22:23], exec, s[22:23]
	s_cbranch_execz .LBB0_456
	s_cmpk_gt_u32 s2, 0x51f
	s_cbranch_scc1 .LBB0_456
	v_add_u32_e32 v66, 0xfffffb60, v138
	v_lshrrev_b32_e32 v64, 6, v66
	v_add_u32_e32 v64, s35, v64
	v_ashrrev_i32_e32 v65, 31, v64
	v_lshlrev_b64 v[64:65], 20, v[64:65]
	v_lshlrev_b32_e32 v66, 14, v66
	v_lshl_add_u64 v[64:65], s[90:91], 0, v[64:65]
	v_and_b32_e32 v188, 0xb0000, v66
	v_lshl_add_u64 v[64:65], v[64:65], 0, v[188:189]
	v_lshlrev_b32_e32 v188, 1, v67
	v_lshl_add_u64 v[64:65], v[64:65], 0, v[188:189]
	v_cmp_ne_u32_e32 vcc, 0, v250
	s_nop 1
	v_cndmask_b32_e32 v240, v61, v60, vcc
	v_cndmask_b32_e32 v241, v63, v62, vcc
	s_nop 1
	v_mov_b32_dpp v242, v240 quad_perm:[1,0,3,2] row_mask:0xf bank_mask:0xf
	v_mov_b32_dpp v243, v241 quad_perm:[1,0,3,2] row_mask:0xf bank_mask:0xf
	s_nop 1
	v_cndmask_b32_e32 v60, v60, v242, vcc
	v_cndmask_b32_e32 v61, v242, v61, vcc
	v_cndmask_b32_e32 v62, v62, v243, vcc
	v_cndmask_b32_e32 v63, v243, v63, vcc
	v_cmp_ne_u32_e32 vcc, 0, v251
	s_nop 1
	v_cndmask_b32_e32 v240, v62, v60, vcc
	v_cndmask_b32_e32 v241, v63, v61, vcc
	s_nop 1
	v_mov_b32_dpp v242, v240 quad_perm:[2,3,0,1] row_mask:0xf bank_mask:0xf
	v_mov_b32_dpp v243, v241 quad_perm:[2,3,0,1] row_mask:0xf bank_mask:0xf
	s_nop 1
	v_cndmask_b32_e32 v60, v60, v242, vcc
	v_cndmask_b32_e32 v62, v242, v62, vcc
	v_cndmask_b32_e32 v61, v61, v243, vcc
	v_cndmask_b32_e32 v63, v243, v63, vcc
	v_cvt_pk_bf16_f32 v244, v60, v61
	v_cvt_pk_bf16_f32 v245, v62, v63
	v_lshl_add_u64 v[248:249], v[64:65], 0, v[246:247]
	global_store_dwordx2 v[248:249], v[244:245], off
	s_nop 1

.LBB0_458:
	s_or_b64 exec, exec, s[22:23]
	s_and_saveexec_b64 s[22:23], s[10:11]
	s_xor_b64 s[22:23], exec, s[22:23]
	s_cbranch_execz .LBB0_461
	s_cmpk_gt_u32 s2, 0x51f
	s_cbranch_scc1 .LBB0_461
	v_add_u32_e32 v62, 0xfffffb70, v138
	v_lshrrev_b32_e32 v60, 6, v62
	v_add_u32_e32 v60, s35, v60
	v_ashrrev_i32_e32 v61, 31, v60
	v_lshlrev_b64 v[60:61], 20, v[60:61]
	v_lshlrev_b32_e32 v62, 14, v62
	v_lshl_add_u64 v[60:61], s[90:91], 0, v[60:61]
	v_and_b32_e32 v188, 0xf0000, v62
	v_lshl_add_u64 v[60:61], v[60:61], 0, v[188:189]
	v_lshlrev_b32_e32 v188, 1, v67
	v_lshl_add_u64 v[60:61], v[60:61], 0, v[188:189]
	v_cmp_ne_u32_e32 vcc, 0, v250
	s_nop 1
	v_cndmask_b32_e32 v240, v57, v56, vcc
	v_cndmask_b32_e32 v241, v59, v58, vcc
	s_nop 1
	v_mov_b32_dpp v242, v240 quad_perm:[1,0,3,2] row_mask:0xf bank_mask:0xf
	v_mov_b32_dpp v243, v241 quad_perm:[1,0,3,2] row_mask:0xf bank_mask:0xf
	s_nop 1
	v_cndmask_b32_e32 v56, v56, v242, vcc
	v_cndmask_b32_e32 v57, v242, v57, vcc
	v_cndmask_b32_e32 v58, v58, v243, vcc
	v_cndmask_b32_e32 v59, v243, v59, vcc
	v_cmp_ne_u32_e32 vcc, 0, v251
	s_nop 1
	v_cndmask_b32_e32 v240, v58, v56, vcc
	v_cndmask_b32_e32 v241, v59, v57, vcc
	s_nop 1
	v_mov_b32_dpp v242, v240 quad_perm:[2,3,0,1] row_mask:0xf bank_mask:0xf
	v_mov_b32_dpp v243, v241 quad_perm:[2,3,0,1] row_mask:0xf bank_mask:0xf
	s_nop 1
	v_cndmask_b32_e32 v56, v56, v242, vcc
	v_cndmask_b32_e32 v58, v242, v58, vcc
	v_cndmask_b32_e32 v57, v57, v243, vcc
	v_cndmask_b32_e32 v59, v243, v59, vcc
	v_cvt_pk_bf16_f32 v244, v56, v57
	v_cvt_pk_bf16_f32 v245, v58, v59
	v_lshl_add_u64 v[248:249], v[60:61], 0, v[246:247]
	global_store_dwordx2 v[248:249], v[244:245], off
	s_nop 1

.LBB0_463:
	s_or_b64 exec, exec, s[22:23]
	s_and_saveexec_b64 s[22:23], s[6:7]
	s_xor_b64 s[22:23], exec, s[22:23]
	s_cbranch_execz .LBB0_466
	s_cmpk_gt_u32 s13, 0x51f
	s_cbranch_scc1 .LBB0_466
	v_add_u32_e32 v58, 0xfffffb60, v120
	v_lshrrev_b32_e32 v56, 6, v58
	v_add_u32_e32 v56, s35, v56
	v_ashrrev_i32_e32 v57, 31, v56
	v_lshlrev_b64 v[56:57], 20, v[56:57]
	v_lshlrev_b32_e32 v58, 14, v58
	v_lshl_add_u64 v[56:57], s[90:91], 0, v[56:57]
	v_and_b32_e32 v188, 0xfc000, v58
	v_lshl_add_u64 v[56:57], v[56:57], 0, v[188:189]
	v_lshlrev_b32_e32 v188, 1, v67
	v_lshl_add_u64 v[56:57], v[56:57], 0, v[188:189]
	v_cmp_ne_u32_e32 vcc, 0, v250
	s_nop 1
	v_cndmask_b32_e32 v240, v53, v52, vcc
	v_cndmask_b32_e32 v241, v55, v54, vcc
	s_nop 1
	v_mov_b32_dpp v242, v240 quad_perm:[1,0,3,2] row_mask:0xf bank_mask:0xf
	v_mov_b32_dpp v243, v241 quad_perm:[1,0,3,2] row_mask:0xf bank_mask:0xf
	s_nop 1
	v_cndmask_b32_e32 v52, v52, v242, vcc
	v_cndmask_b32_e32 v53, v242, v53, vcc
	v_cndmask_b32_e32 v54, v54, v243, vcc
	v_cndmask_b32_e32 v55, v243, v55, vcc
	v_cmp_ne_u32_e32 vcc, 0, v251
	s_nop 1
	v_cndmask_b32_e32 v240, v54, v52, vcc
	v_cndmask_b32_e32 v241, v55, v53, vcc
	s_nop 1
	v_mov_b32_dpp v242, v240 quad_perm:[2,3,0,1] row_mask:0xf bank_mask:0xf
	v_mov_b32_dpp v243, v241 quad_perm:[2,3,0,1] row_mask:0xf bank_mask:0xf
	s_nop 1
	v_cndmask_b32_e32 v52, v52, v242, vcc
	v_cndmask_b32_e32 v54, v242, v54, vcc
	v_cndmask_b32_e32 v53, v53, v243, vcc
	v_cndmask_b32_e32 v55, v243, v55, vcc
	v_cvt_pk_bf16_f32 v244, v52, v53
	v_cvt_pk_bf16_f32 v245, v54, v55
	v_lshl_add_u64 v[248:249], v[56:57], 0, v[246:247]
	global_store_dwordx2 v[248:249], v[244:245], off
	s_nop 1

.LBB0_468:
	s_or_b64 exec, exec, s[22:23]
	s_and_saveexec_b64 s[22:23], s[8:9]
	s_xor_b64 s[22:23], exec, s[22:23]
	s_cbranch_execz .LBB0_471
	s_cmpk_gt_u32 s15, 0x51f
	s_cbranch_scc1 .LBB0_471
	v_add_u32_e32 v54, 0xfffffb60, v116
	v_lshrrev_b32_e32 v52, 6, v54
	v_add_u32_e32 v52, s35, v52
	v_ashrrev_i32_e32 v53, 31, v52
	v_lshlrev_b64 v[52:53], 20, v[52:53]
	v_lshlrev_b32_e32 v54, 14, v54
	v_lshl_add_u64 v[52:53], s[90:91], 0, v[52:53]
	v_and_b32_e32 v188, 0xfc000, v54
	v_lshl_add_u64 v[52:53], v[52:53], 0, v[188:189]
	v_lshlrev_b32_e32 v188, 1, v67
	v_lshl_add_u64 v[52:53], v[52:53], 0, v[188:189]
	v_cmp_ne_u32_e32 vcc, 0, v250
	s_nop 1
	v_cndmask_b32_e32 v240, v49, v48, vcc
	v_cndmask_b32_e32 v241, v51, v50, vcc
	s_nop 1
	v_mov_b32_dpp v242, v240 quad_perm:[1,0,3,2] row_mask:0xf bank_mask:0xf
	v_mov_b32_dpp v243, v241 quad_perm:[1,0,3,2] row_mask:0xf bank_mask:0xf
	s_nop 1
	v_cndmask_b32_e32 v48, v48, v242, vcc
	v_cndmask_b32_e32 v49, v242, v49, vcc
	v_cndmask_b32_e32 v50, v50, v243, vcc
	v_cndmask_b32_e32 v51, v243, v51, vcc
	v_cmp_ne_u32_e32 vcc, 0, v251
	s_nop 1
	v_cndmask_b32_e32 v240, v50, v48, vcc
	v_cndmask_b32_e32 v241, v51, v49, vcc
	s_nop 1
	v_mov_b32_dpp v242, v240 quad_perm:[2,3,0,1] row_mask:0xf bank_mask:0xf
	v_mov_b32_dpp v243, v241 quad_perm:[2,3,0,1] row_mask:0xf bank_mask:0xf
	s_nop 1
	v_cndmask_b32_e32 v48, v48, v242, vcc
	v_cndmask_b32_e32 v50, v242, v50, vcc
	v_cndmask_b32_e32 v49, v49, v243, vcc
	v_cndmask_b32_e32 v51, v243, v51, vcc
	v_cvt_pk_bf16_f32 v244, v48, v49
	v_cvt_pk_bf16_f32 v245, v50, v51
	v_lshl_add_u64 v[248:249], v[52:53], 0, v[246:247]
	global_store_dwordx2 v[248:249], v[244:245], off
	s_nop 1

.LBB0_473:
	s_or_b64 exec, exec, s[22:23]
	s_movk_i32 s3, 0x1fdf
	v_bitop3_b32 v50, v66, s3, 16 bitop3:0xc8
	s_and_saveexec_b64 s[22:23], s[4:5]
	s_xor_b64 s[22:23], exec, s[22:23]
	s_cbranch_execz .LBB0_476
	s_cmpk_gt_u32 s2, 0x51f
	s_cbranch_scc1 .LBB0_476
	v_add_u32_e32 v51, 0xfffffb60, v138
	v_lshrrev_b32_e32 v48, 6, v51
	v_add_u32_e32 v48, s35, v48
	v_ashrrev_i32_e32 v49, 31, v48
	v_lshlrev_b64 v[48:49], 20, v[48:49]
	v_lshlrev_b32_e32 v51, 14, v51
	v_lshl_add_u64 v[48:49], s[90:91], 0, v[48:49]
	v_and_b32_e32 v188, 0xb0000, v51
	v_lshl_add_u64 v[48:49], v[48:49], 0, v[188:189]
	v_lshlrev_b32_e32 v188, 1, v50
	v_lshl_add_u64 v[48:49], v[48:49], 0, v[188:189]
	v_cmp_ne_u32_e32 vcc, 0, v250
	s_nop 1
	v_cndmask_b32_e32 v240, v45, v44, vcc
	v_cndmask_b32_e32 v241, v47, v46, vcc
	s_nop 1
	v_mov_b32_dpp v242, v240 quad_perm:[1,0,3,2] row_mask:0xf bank_mask:0xf
	v_mov_b32_dpp v243, v241 quad_perm:[1,0,3,2] row_mask:0xf bank_mask:0xf
	s_nop 1
	v_cndmask_b32_e32 v44, v44, v242, vcc
	v_cndmask_b32_e32 v45, v242, v45, vcc
	v_cndmask_b32_e32 v46, v46, v243, vcc
	v_cndmask_b32_e32 v47, v243, v47, vcc
	v_cmp_ne_u32_e32 vcc, 0, v251
	s_nop 1
	v_cndmask_b32_e32 v240, v46, v44, vcc
	v_cndmask_b32_e32 v241, v47, v45, vcc
	s_nop 1
	v_mov_b32_dpp v242, v240 quad_perm:[2,3,0,1] row_mask:0xf bank_mask:0xf
	v_mov_b32_dpp v243, v241 quad_perm:[2,3,0,1] row_mask:0xf bank_mask:0xf
	s_nop 1
	v_cndmask_b32_e32 v44, v44, v242, vcc
	v_cndmask_b32_e32 v46, v242, v46, vcc
	v_cndmask_b32_e32 v45, v45, v243, vcc
	v_cndmask_b32_e32 v47, v243, v47, vcc
	v_cvt_pk_bf16_f32 v244, v44, v45
	v_cvt_pk_bf16_f32 v245, v46, v47
	v_lshl_add_u64 v[248:249], v[48:49], 0, v[246:247]
	global_store_dwordx2 v[248:249], v[244:245], off
	s_nop 1

.LBB0_478:
	s_or_b64 exec, exec, s[22:23]
	s_and_saveexec_b64 s[22:23], s[10:11]
	s_xor_b64 s[22:23], exec, s[22:23]
	s_cbranch_execz .LBB0_481
	s_cmpk_gt_u32 s2, 0x51f
	s_cbranch_scc1 .LBB0_481
	v_add_u32_e32 v46, 0xfffffb70, v138
	v_lshrrev_b32_e32 v44, 6, v46
	v_add_u32_e32 v44, s35, v44
	v_ashrrev_i32_e32 v45, 31, v44
	v_lshlrev_b64 v[44:45], 20, v[44:45]
	v_lshlrev_b32_e32 v46, 14, v46
	v_lshl_add_u64 v[44:45], s[90:91], 0, v[44:45]
	v_and_b32_e32 v188, 0xf0000, v46
	v_lshl_add_u64 v[44:45], v[44:45], 0, v[188:189]
	v_lshlrev_b32_e32 v188, 1, v50
	v_lshl_add_u64 v[44:45], v[44:45], 0, v[188:189]
	v_cmp_ne_u32_e32 vcc, 0, v250
	s_nop 1
	v_cndmask_b32_e32 v240, v41, v40, vcc
	v_cndmask_b32_e32 v241, v43, v42, vcc
	s_nop 1
	v_mov_b32_dpp v242, v240 quad_perm:[1,0,3,2] row_mask:0xf bank_mask:0xf
	v_mov_b32_dpp v243, v241 quad_perm:[1,0,3,2] row_mask:0xf bank_mask:0xf
	s_nop 1
	v_cndmask_b32_e32 v40, v40, v242, vcc
	v_cndmask_b32_e32 v41, v242, v41, vcc
	v_cndmask_b32_e32 v42, v42, v243, vcc
	v_cndmask_b32_e32 v43, v243, v43, vcc
	v_cmp_ne_u32_e32 vcc, 0, v251
	s_nop 1
	v_cndmask_b32_e32 v240, v42, v40, vcc
	v_cndmask_b32_e32 v241, v43, v41, vcc
	s_nop 1
	v_mov_b32_dpp v242, v240 quad_perm:[2,3,0,1] row_mask:0xf bank_mask:0xf
	v_mov_b32_dpp v243, v241 quad_perm:[2,3,0,1] row_mask:0xf bank_mask:0xf
	s_nop 1
	v_cndmask_b32_e32 v40, v40, v242, vcc
	v_cndmask_b32_e32 v42, v242, v42, vcc
	v_cndmask_b32_e32 v41, v41, v243, vcc
	v_cndmask_b32_e32 v43, v243, v43, vcc
	v_cvt_pk_bf16_f32 v244, v40, v41
	v_cvt_pk_bf16_f32 v245, v42, v43
	v_lshl_add_u64 v[248:249], v[44:45], 0, v[246:247]
	global_store_dwordx2 v[248:249], v[244:245], off
	s_nop 1

.LBB0_483:
	s_or_b64 exec, exec, s[22:23]
	s_and_saveexec_b64 s[22:23], s[6:7]
	s_xor_b64 s[22:23], exec, s[22:23]
	s_cbranch_execz .LBB0_486
	s_cmpk_gt_u32 s13, 0x51f
	s_cbranch_scc1 .LBB0_486
	v_add_u32_e32 v42, 0xfffffb60, v120
	v_lshrrev_b32_e32 v40, 6, v42
	v_add_u32_e32 v40, s35, v40
	v_ashrrev_i32_e32 v41, 31, v40
	v_lshlrev_b64 v[40:41], 20, v[40:41]
	v_lshlrev_b32_e32 v42, 14, v42
	v_lshl_add_u64 v[40:41], s[90:91], 0, v[40:41]
	v_and_b32_e32 v188, 0xfc000, v42
	v_lshl_add_u64 v[40:41], v[40:41], 0, v[188:189]
	v_lshlrev_b32_e32 v188, 1, v50
	v_lshl_add_u64 v[40:41], v[40:41], 0, v[188:189]
	v_cmp_ne_u32_e32 vcc, 0, v250
	s_nop 1
	v_cndmask_b32_e32 v240, v37, v36, vcc
	v_cndmask_b32_e32 v241, v39, v38, vcc
	s_nop 1
	v_mov_b32_dpp v242, v240 quad_perm:[1,0,3,2] row_mask:0xf bank_mask:0xf
	v_mov_b32_dpp v243, v241 quad_perm:[1,0,3,2] row_mask:0xf bank_mask:0xf
	s_nop 1
	v_cndmask_b32_e32 v36, v36, v242, vcc
	v_cndmask_b32_e32 v37, v242, v37, vcc
	v_cndmask_b32_e32 v38, v38, v243, vcc
	v_cndmask_b32_e32 v39, v243, v39, vcc
	v_cmp_ne_u32_e32 vcc, 0, v251
	s_nop 1
	v_cndmask_b32_e32 v240, v38, v36, vcc
	v_cndmask_b32_e32 v241, v39, v37, vcc
	s_nop 1
	v_mov_b32_dpp v242, v240 quad_perm:[2,3,0,1] row_mask:0xf bank_mask:0xf
	v_mov_b32_dpp v243, v241 quad_perm:[2,3,0,1] row_mask:0xf bank_mask:0xf
	s_nop 1
	v_cndmask_b32_e32 v36, v36, v242, vcc
	v_cndmask_b32_e32 v38, v242, v38, vcc
	v_cndmask_b32_e32 v37, v37, v243, vcc
	v_cndmask_b32_e32 v39, v243, v39, vcc
	v_cvt_pk_bf16_f32 v244, v36, v37
	v_cvt_pk_bf16_f32 v245, v38, v39
	v_lshl_add_u64 v[248:249], v[40:41], 0, v[246:247]
	global_store_dwordx2 v[248:249], v[244:245], off
	s_nop 1

.LBB0_488:
	s_or_b64 exec, exec, s[22:23]
	s_and_saveexec_b64 s[22:23], s[8:9]
	s_xor_b64 s[22:23], exec, s[22:23]
	s_cbranch_execz .LBB0_491
	s_cmpk_gt_u32 s15, 0x51f
	s_cbranch_scc1 .LBB0_491
	v_add_u32_e32 v38, 0xfffffb60, v116
	v_lshrrev_b32_e32 v36, 6, v38
	v_add_u32_e32 v36, s35, v36
	v_ashrrev_i32_e32 v37, 31, v36
	v_lshlrev_b64 v[36:37], 20, v[36:37]
	v_lshlrev_b32_e32 v38, 14, v38
	v_lshl_add_u64 v[36:37], s[90:91], 0, v[36:37]
	v_and_b32_e32 v188, 0xfc000, v38
	v_lshl_add_u64 v[36:37], v[36:37], 0, v[188:189]
	v_lshlrev_b32_e32 v188, 1, v50
	v_lshl_add_u64 v[36:37], v[36:37], 0, v[188:189]
	v_cmp_ne_u32_e32 vcc, 0, v250
	s_nop 1
	v_cndmask_b32_e32 v240, v33, v32, vcc
	v_cndmask_b32_e32 v241, v35, v34, vcc
	s_nop 1
	v_mov_b32_dpp v242, v240 quad_perm:[1,0,3,2] row_mask:0xf bank_mask:0xf
	v_mov_b32_dpp v243, v241 quad_perm:[1,0,3,2] row_mask:0xf bank_mask:0xf
	s_nop 1
	v_cndmask_b32_e32 v32, v32, v242, vcc
	v_cndmask_b32_e32 v33, v242, v33, vcc
	v_cndmask_b32_e32 v34, v34, v243, vcc
	v_cndmask_b32_e32 v35, v243, v35, vcc
	v_cmp_ne_u32_e32 vcc, 0, v251
	s_nop 1
	v_cndmask_b32_e32 v240, v34, v32, vcc
	v_cndmask_b32_e32 v241, v35, v33, vcc
	s_nop 1
	v_mov_b32_dpp v242, v240 quad_perm:[2,3,0,1] row_mask:0xf bank_mask:0xf
	v_mov_b32_dpp v243, v241 quad_perm:[2,3,0,1] row_mask:0xf bank_mask:0xf
	s_nop 1
	v_cndmask_b32_e32 v32, v32, v242, vcc
	v_cndmask_b32_e32 v34, v242, v34, vcc
	v_cndmask_b32_e32 v33, v33, v243, vcc
	v_cndmask_b32_e32 v35, v243, v35, vcc
	v_cvt_pk_bf16_f32 v244, v32, v33
	v_cvt_pk_bf16_f32 v245, v34, v35
	v_lshl_add_u64 v[248:249], v[36:37], 0, v[246:247]
	global_store_dwordx2 v[248:249], v[244:245], off
	s_nop 1

.LBB0_493:
	s_or_b64 exec, exec, s[22:23]
	s_movk_i32 s3, 0x1fef
	v_bitop3_b32 v34, v66, s3, 32 bitop3:0xc8
	s_and_saveexec_b64 s[22:23], s[4:5]
	s_xor_b64 s[22:23], exec, s[22:23]
	s_cbranch_execz .LBB0_496
	s_cmpk_gt_u32 s2, 0x51f
	s_cbranch_scc1 .LBB0_496
	v_add_u32_e32 v35, 0xfffffb60, v138
	v_lshrrev_b32_e32 v32, 6, v35
	v_add_u32_e32 v32, s35, v32
	v_ashrrev_i32_e32 v33, 31, v32
	v_lshlrev_b64 v[32:33], 20, v[32:33]
	v_lshlrev_b32_e32 v35, 14, v35
	v_lshl_add_u64 v[32:33], s[90:91], 0, v[32:33]
	v_and_b32_e32 v188, 0xb0000, v35
	v_lshl_add_u64 v[32:33], v[32:33], 0, v[188:189]
	v_lshlrev_b32_e32 v188, 1, v34
	v_lshl_add_u64 v[32:33], v[32:33], 0, v[188:189]
	v_cmp_ne_u32_e32 vcc, 0, v250
	s_nop 1
	v_cndmask_b32_e32 v240, v29, v28, vcc
	v_cndmask_b32_e32 v241, v31, v30, vcc
	s_nop 1
	v_mov_b32_dpp v242, v240 quad_perm:[1,0,3,2] row_mask:0xf bank_mask:0xf
	v_mov_b32_dpp v243, v241 quad_perm:[1,0,3,2] row_mask:0xf bank_mask:0xf
	s_nop 1
	v_cndmask_b32_e32 v28, v28, v242, vcc
	v_cndmask_b32_e32 v29, v242, v29, vcc
	v_cndmask_b32_e32 v30, v30, v243, vcc
	v_cndmask_b32_e32 v31, v243, v31, vcc
	v_cmp_ne_u32_e32 vcc, 0, v251
	s_nop 1
	v_cndmask_b32_e32 v240, v30, v28, vcc
	v_cndmask_b32_e32 v241, v31, v29, vcc
	s_nop 1
	v_mov_b32_dpp v242, v240 quad_perm:[2,3,0,1] row_mask:0xf bank_mask:0xf
	v_mov_b32_dpp v243, v241 quad_perm:[2,3,0,1] row_mask:0xf bank_mask:0xf
	s_nop 1
	v_cndmask_b32_e32 v28, v28, v242, vcc
	v_cndmask_b32_e32 v30, v242, v30, vcc
	v_cndmask_b32_e32 v29, v29, v243, vcc
	v_cndmask_b32_e32 v31, v243, v31, vcc
	v_cvt_pk_bf16_f32 v244, v28, v29
	v_cvt_pk_bf16_f32 v245, v30, v31
	v_lshl_add_u64 v[248:249], v[32:33], 0, v[246:247]
	global_store_dwordx2 v[248:249], v[244:245], off
	s_nop 1

.LBB0_498:
	s_or_b64 exec, exec, s[22:23]
	s_and_saveexec_b64 s[22:23], s[10:11]
	s_xor_b64 s[22:23], exec, s[22:23]
	s_cbranch_execz .LBB0_501
	s_cmpk_gt_u32 s2, 0x51f
	s_cbranch_scc1 .LBB0_501
	v_add_u32_e32 v30, 0xfffffb70, v138
	v_lshrrev_b32_e32 v28, 6, v30
	v_add_u32_e32 v28, s35, v28
	v_ashrrev_i32_e32 v29, 31, v28
	v_lshlrev_b64 v[28:29], 20, v[28:29]
	v_lshlrev_b32_e32 v30, 14, v30
	v_lshl_add_u64 v[28:29], s[90:91], 0, v[28:29]
	v_and_b32_e32 v188, 0xf0000, v30
	v_lshl_add_u64 v[28:29], v[28:29], 0, v[188:189]
	v_lshlrev_b32_e32 v188, 1, v34
	v_lshl_add_u64 v[28:29], v[28:29], 0, v[188:189]
	v_cmp_ne_u32_e32 vcc, 0, v250
	s_nop 1
	v_cndmask_b32_e32 v240, v25, v24, vcc
	v_cndmask_b32_e32 v241, v27, v26, vcc
	s_nop 1
	v_mov_b32_dpp v242, v240 quad_perm:[1,0,3,2] row_mask:0xf bank_mask:0xf
	v_mov_b32_dpp v243, v241 quad_perm:[1,0,3,2] row_mask:0xf bank_mask:0xf
	s_nop 1
	v_cndmask_b32_e32 v24, v24, v242, vcc
	v_cndmask_b32_e32 v25, v242, v25, vcc
	v_cndmask_b32_e32 v26, v26, v243, vcc
	v_cndmask_b32_e32 v27, v243, v27, vcc
	v_cmp_ne_u32_e32 vcc, 0, v251
	s_nop 1
	v_cndmask_b32_e32 v240, v26, v24, vcc
	v_cndmask_b32_e32 v241, v27, v25, vcc
	s_nop 1
	v_mov_b32_dpp v242, v240 quad_perm:[2,3,0,1] row_mask:0xf bank_mask:0xf
	v_mov_b32_dpp v243, v241 quad_perm:[2,3,0,1] row_mask:0xf bank_mask:0xf
	s_nop 1
	v_cndmask_b32_e32 v24, v24, v242, vcc
	v_cndmask_b32_e32 v26, v242, v26, vcc
	v_cndmask_b32_e32 v25, v25, v243, vcc
	v_cndmask_b32_e32 v27, v243, v27, vcc
	v_cvt_pk_bf16_f32 v244, v24, v25
	v_cvt_pk_bf16_f32 v245, v26, v27
	v_lshl_add_u64 v[248:249], v[28:29], 0, v[246:247]
	global_store_dwordx2 v[248:249], v[244:245], off
	s_nop 1

.LBB0_503:
	s_or_b64 exec, exec, s[22:23]
	s_and_saveexec_b64 s[22:23], s[6:7]
	s_xor_b64 s[22:23], exec, s[22:23]
	s_cbranch_execz .LBB0_506
	s_cmpk_gt_u32 s13, 0x51f
	s_cbranch_scc1 .LBB0_506
	v_add_u32_e32 v26, 0xfffffb60, v120
	v_lshrrev_b32_e32 v24, 6, v26
	v_add_u32_e32 v24, s35, v24
	v_ashrrev_i32_e32 v25, 31, v24
	v_lshlrev_b64 v[24:25], 20, v[24:25]
	v_lshlrev_b32_e32 v26, 14, v26
	v_lshl_add_u64 v[24:25], s[90:91], 0, v[24:25]
	v_and_b32_e32 v188, 0xfc000, v26
	v_lshl_add_u64 v[24:25], v[24:25], 0, v[188:189]
	v_lshlrev_b32_e32 v188, 1, v34
	v_lshl_add_u64 v[24:25], v[24:25], 0, v[188:189]
	v_cmp_ne_u32_e32 vcc, 0, v250
	s_nop 1
	v_cndmask_b32_e32 v240, v21, v20, vcc
	v_cndmask_b32_e32 v241, v23, v22, vcc
	s_nop 1
	v_mov_b32_dpp v242, v240 quad_perm:[1,0,3,2] row_mask:0xf bank_mask:0xf
	v_mov_b32_dpp v243, v241 quad_perm:[1,0,3,2] row_mask:0xf bank_mask:0xf
	s_nop 1
	v_cndmask_b32_e32 v20, v20, v242, vcc
	v_cndmask_b32_e32 v21, v242, v21, vcc
	v_cndmask_b32_e32 v22, v22, v243, vcc
	v_cndmask_b32_e32 v23, v243, v23, vcc
	v_cmp_ne_u32_e32 vcc, 0, v251
	s_nop 1
	v_cndmask_b32_e32 v240, v22, v20, vcc
	v_cndmask_b32_e32 v241, v23, v21, vcc
	s_nop 1
	v_mov_b32_dpp v242, v240 quad_perm:[2,3,0,1] row_mask:0xf bank_mask:0xf
	v_mov_b32_dpp v243, v241 quad_perm:[2,3,0,1] row_mask:0xf bank_mask:0xf
	s_nop 1
	v_cndmask_b32_e32 v20, v20, v242, vcc
	v_cndmask_b32_e32 v22, v242, v22, vcc
	v_cndmask_b32_e32 v21, v21, v243, vcc
	v_cndmask_b32_e32 v23, v243, v23, vcc
	v_cvt_pk_bf16_f32 v244, v20, v21
	v_cvt_pk_bf16_f32 v245, v22, v23
	v_lshl_add_u64 v[248:249], v[24:25], 0, v[246:247]
	global_store_dwordx2 v[248:249], v[244:245], off
	s_nop 1

.LBB0_508:
	s_or_b64 exec, exec, s[22:23]
	s_and_saveexec_b64 s[22:23], s[8:9]
	s_xor_b64 s[22:23], exec, s[22:23]
	s_cbranch_execz .LBB0_511
	s_cmpk_gt_u32 s15, 0x51f
	s_cbranch_scc1 .LBB0_511
	v_add_u32_e32 v22, 0xfffffb60, v116
	v_lshrrev_b32_e32 v20, 6, v22
	v_add_u32_e32 v20, s35, v20
	v_ashrrev_i32_e32 v21, 31, v20
	v_lshlrev_b64 v[20:21], 20, v[20:21]
	v_lshlrev_b32_e32 v22, 14, v22
	v_lshl_add_u64 v[20:21], s[90:91], 0, v[20:21]
	v_and_b32_e32 v188, 0xfc000, v22
	v_lshl_add_u64 v[20:21], v[20:21], 0, v[188:189]
	v_lshlrev_b32_e32 v188, 1, v34
	v_lshl_add_u64 v[20:21], v[20:21], 0, v[188:189]
	v_cmp_ne_u32_e32 vcc, 0, v250
	s_nop 1
	v_cndmask_b32_e32 v240, v17, v16, vcc
	v_cndmask_b32_e32 v241, v19, v18, vcc
	s_nop 1
	v_mov_b32_dpp v242, v240 quad_perm:[1,0,3,2] row_mask:0xf bank_mask:0xf
	v_mov_b32_dpp v243, v241 quad_perm:[1,0,3,2] row_mask:0xf bank_mask:0xf
	s_nop 1
	v_cndmask_b32_e32 v16, v16, v242, vcc
	v_cndmask_b32_e32 v17, v242, v17, vcc
	v_cndmask_b32_e32 v18, v18, v243, vcc
	v_cndmask_b32_e32 v19, v243, v19, vcc
	v_cmp_ne_u32_e32 vcc, 0, v251
	s_nop 1
	v_cndmask_b32_e32 v240, v18, v16, vcc
	v_cndmask_b32_e32 v241, v19, v17, vcc
	s_nop 1
	v_mov_b32_dpp v242, v240 quad_perm:[2,3,0,1] row_mask:0xf bank_mask:0xf
	v_mov_b32_dpp v243, v241 quad_perm:[2,3,0,1] row_mask:0xf bank_mask:0xf
	s_nop 1
	v_cndmask_b32_e32 v16, v16, v242, vcc
	v_cndmask_b32_e32 v18, v242, v18, vcc
	v_cndmask_b32_e32 v17, v17, v243, vcc
	v_cndmask_b32_e32 v19, v243, v19, vcc
	v_cvt_pk_bf16_f32 v244, v16, v17
	v_cvt_pk_bf16_f32 v245, v18, v19
	v_lshl_add_u64 v[248:249], v[20:21], 0, v[246:247]
	global_store_dwordx2 v[248:249], v[244:245], off
	s_nop 1

.LBB0_513:
	s_or_b64 exec, exec, s[22:23]
	s_movk_i32 s3, 0x1fff
	v_bitop3_b32 v18, v66, s3, 48 bitop3:0xc8
	s_and_saveexec_b64 s[22:23], s[4:5]
	s_xor_b64 s[4:5], exec, s[22:23]
	s_cbranch_execz .LBB0_516
	s_cmpk_gt_u32 s2, 0x51f
	s_cbranch_scc1 .LBB0_516
	v_add_u32_e32 v19, 0xfffffb60, v138
	v_lshrrev_b32_e32 v16, 6, v19
	v_add_u32_e32 v16, s35, v16
	v_ashrrev_i32_e32 v17, 31, v16
	v_lshlrev_b64 v[16:17], 20, v[16:17]
	v_lshlrev_b32_e32 v19, 14, v19
	v_lshl_add_u64 v[16:17], s[90:91], 0, v[16:17]
	v_and_b32_e32 v188, 0xb0000, v19
	v_lshl_add_u64 v[16:17], v[16:17], 0, v[188:189]
	v_lshlrev_b32_e32 v188, 1, v18
	v_lshl_add_u64 v[16:17], v[16:17], 0, v[188:189]
	v_cmp_ne_u32_e32 vcc, 0, v250
	s_nop 1
	v_cndmask_b32_e32 v240, v13, v12, vcc
	v_cndmask_b32_e32 v241, v15, v14, vcc
	s_nop 1
	v_mov_b32_dpp v242, v240 quad_perm:[1,0,3,2] row_mask:0xf bank_mask:0xf
	v_mov_b32_dpp v243, v241 quad_perm:[1,0,3,2] row_mask:0xf bank_mask:0xf
	s_nop 1
	v_cndmask_b32_e32 v12, v12, v242, vcc
	v_cndmask_b32_e32 v13, v242, v13, vcc
	v_cndmask_b32_e32 v14, v14, v243, vcc
	v_cndmask_b32_e32 v15, v243, v15, vcc
	v_cmp_ne_u32_e32 vcc, 0, v251
	s_nop 1
	v_cndmask_b32_e32 v240, v14, v12, vcc
	v_cndmask_b32_e32 v241, v15, v13, vcc
	s_nop 1
	v_mov_b32_dpp v242, v240 quad_perm:[2,3,0,1] row_mask:0xf bank_mask:0xf
	v_mov_b32_dpp v243, v241 quad_perm:[2,3,0,1] row_mask:0xf bank_mask:0xf
	s_nop 1
	v_cndmask_b32_e32 v12, v12, v242, vcc
	v_cndmask_b32_e32 v14, v242, v14, vcc
	v_cndmask_b32_e32 v13, v13, v243, vcc
	v_cndmask_b32_e32 v15, v243, v15, vcc
	v_cvt_pk_bf16_f32 v244, v12, v13
	v_cvt_pk_bf16_f32 v245, v14, v15
	v_lshl_add_u64 v[248:249], v[16:17], 0, v[246:247]
	global_store_dwordx2 v[248:249], v[244:245], off
	s_nop 1

.LBB0_518:
	s_or_b64 exec, exec, s[4:5]
	s_and_saveexec_b64 s[4:5], s[10:11]
	s_xor_b64 s[4:5], exec, s[4:5]
	s_cbranch_execz .LBB0_521
	s_cmpk_gt_u32 s2, 0x51f
	s_cbranch_scc1 .LBB0_521
	v_add_u32_e32 v14, 0xfffffb70, v138
	v_lshrrev_b32_e32 v12, 6, v14
	v_add_u32_e32 v12, s35, v12
	v_ashrrev_i32_e32 v13, 31, v12
	v_lshlrev_b64 v[12:13], 20, v[12:13]
	v_lshlrev_b32_e32 v14, 14, v14
	v_lshl_add_u64 v[12:13], s[90:91], 0, v[12:13]
	v_and_b32_e32 v188, 0xf0000, v14
	v_lshl_add_u64 v[12:13], v[12:13], 0, v[188:189]
	v_lshlrev_b32_e32 v188, 1, v18
	v_lshl_add_u64 v[12:13], v[12:13], 0, v[188:189]
	v_cmp_ne_u32_e32 vcc, 0, v250
	s_nop 1
	v_cndmask_b32_e32 v240, v9, v8, vcc
	v_cndmask_b32_e32 v241, v11, v10, vcc
	s_nop 1
	v_mov_b32_dpp v242, v240 quad_perm:[1,0,3,2] row_mask:0xf bank_mask:0xf
	v_mov_b32_dpp v243, v241 quad_perm:[1,0,3,2] row_mask:0xf bank_mask:0xf
	s_nop 1
	v_cndmask_b32_e32 v8, v8, v242, vcc
	v_cndmask_b32_e32 v9, v242, v9, vcc
	v_cndmask_b32_e32 v10, v10, v243, vcc
	v_cndmask_b32_e32 v11, v243, v11, vcc
	v_cmp_ne_u32_e32 vcc, 0, v251
	s_nop 1
	v_cndmask_b32_e32 v240, v10, v8, vcc
	v_cndmask_b32_e32 v241, v11, v9, vcc
	s_nop 1
	v_mov_b32_dpp v242, v240 quad_perm:[2,3,0,1] row_mask:0xf bank_mask:0xf
	v_mov_b32_dpp v243, v241 quad_perm:[2,3,0,1] row_mask:0xf bank_mask:0xf
	s_nop 1
	v_cndmask_b32_e32 v8, v8, v242, vcc
	v_cndmask_b32_e32 v10, v242, v10, vcc
	v_cndmask_b32_e32 v9, v9, v243, vcc
	v_cndmask_b32_e32 v11, v243, v11, vcc
	v_cvt_pk_bf16_f32 v244, v8, v9
	v_cvt_pk_bf16_f32 v245, v10, v11
	v_lshl_add_u64 v[248:249], v[12:13], 0, v[246:247]
	global_store_dwordx2 v[248:249], v[244:245], off
	s_nop 1

.LBB0_523:
	s_or_b64 exec, exec, s[4:5]
	s_and_saveexec_b64 s[4:5], s[6:7]
	s_xor_b64 s[4:5], exec, s[4:5]
	s_cbranch_execz .LBB0_526
	s_cmpk_gt_u32 s13, 0x51f
	s_cbranch_scc1 .LBB0_526
	v_add_u32_e32 v10, 0xfffffb60, v120
	v_lshrrev_b32_e32 v8, 6, v10
	v_add_u32_e32 v8, s35, v8
	v_ashrrev_i32_e32 v9, 31, v8
	v_lshlrev_b64 v[8:9], 20, v[8:9]
	v_lshlrev_b32_e32 v10, 14, v10
	v_lshl_add_u64 v[8:9], s[90:91], 0, v[8:9]
	v_and_b32_e32 v188, 0xfc000, v10
	v_lshl_add_u64 v[8:9], v[8:9], 0, v[188:189]
	v_lshlrev_b32_e32 v188, 1, v18
	v_lshl_add_u64 v[8:9], v[8:9], 0, v[188:189]
	v_cmp_ne_u32_e32 vcc, 0, v250
	s_nop 1
	v_cndmask_b32_e32 v240, v5, v4, vcc
	v_cndmask_b32_e32 v241, v7, v6, vcc
	s_nop 1
	v_mov_b32_dpp v242, v240 quad_perm:[1,0,3,2] row_mask:0xf bank_mask:0xf
	v_mov_b32_dpp v243, v241 quad_perm:[1,0,3,2] row_mask:0xf bank_mask:0xf
	s_nop 1
	v_cndmask_b32_e32 v4, v4, v242, vcc
	v_cndmask_b32_e32 v5, v242, v5, vcc
	v_cndmask_b32_e32 v6, v6, v243, vcc
	v_cndmask_b32_e32 v7, v243, v7, vcc
	v_cmp_ne_u32_e32 vcc, 0, v251
	s_nop 1
	v_cndmask_b32_e32 v240, v6, v4, vcc
	v_cndmask_b32_e32 v241, v7, v5, vcc
	s_nop 1
	v_mov_b32_dpp v242, v240 quad_perm:[2,3,0,1] row_mask:0xf bank_mask:0xf
	v_mov_b32_dpp v243, v241 quad_perm:[2,3,0,1] row_mask:0xf bank_mask:0xf
	s_nop 1
	v_cndmask_b32_e32 v4, v4, v242, vcc
	v_cndmask_b32_e32 v6, v242, v6, vcc
	v_cndmask_b32_e32 v5, v5, v243, vcc
	v_cndmask_b32_e32 v7, v243, v7, vcc
	v_cvt_pk_bf16_f32 v244, v4, v5
	v_cvt_pk_bf16_f32 v245, v6, v7
	v_lshl_add_u64 v[248:249], v[8:9], 0, v[246:247]
	global_store_dwordx2 v[248:249], v[244:245], off
	s_nop 1

.LBB0_528:
	s_or_b64 exec, exec, s[4:5]
	s_and_saveexec_b64 s[4:5], s[8:9]
	s_xor_b64 s[4:5], exec, s[4:5]
	s_cbranch_execz .LBB0_531
	s_cmpk_gt_u32 s15, 0x51f
	s_cbranch_scc1 .LBB0_531
	v_add_u32_e32 v6, 0xfffffb60, v116
	v_lshrrev_b32_e32 v4, 6, v6
	v_add_u32_e32 v4, s35, v4
	v_ashrrev_i32_e32 v5, 31, v4
	v_lshlrev_b64 v[4:5], 20, v[4:5]
	v_lshlrev_b32_e32 v6, 14, v6
	v_lshl_add_u64 v[4:5], s[90:91], 0, v[4:5]
	v_and_b32_e32 v188, 0xfc000, v6
	v_lshl_add_u64 v[4:5], v[4:5], 0, v[188:189]
	v_lshlrev_b32_e32 v188, 1, v18
	v_lshl_add_u64 v[4:5], v[4:5], 0, v[188:189]
	v_cmp_ne_u32_e32 vcc, 0, v250
	s_nop 1
	v_cndmask_b32_e32 v240, v1, v0, vcc
	v_cndmask_b32_e32 v241, v3, v2, vcc
	s_nop 1
	v_mov_b32_dpp v242, v240 quad_perm:[1,0,3,2] row_mask:0xf bank_mask:0xf
	v_mov_b32_dpp v243, v241 quad_perm:[1,0,3,2] row_mask:0xf bank_mask:0xf
	s_nop 1
	v_cndmask_b32_e32 v0, v0, v242, vcc
	v_cndmask_b32_e32 v1, v242, v1, vcc
	v_cndmask_b32_e32 v2, v2, v243, vcc
	v_cndmask_b32_e32 v3, v243, v3, vcc
	v_cmp_ne_u32_e32 vcc, 0, v251
	s_nop 1
	v_cndmask_b32_e32 v240, v2, v0, vcc
	v_cndmask_b32_e32 v241, v3, v1, vcc
	s_nop 1
	v_mov_b32_dpp v242, v240 quad_perm:[2,3,0,1] row_mask:0xf bank_mask:0xf
	v_mov_b32_dpp v243, v241 quad_perm:[2,3,0,1] row_mask:0xf bank_mask:0xf
	s_nop 1
	v_cndmask_b32_e32 v0, v0, v242, vcc
	v_cndmask_b32_e32 v2, v242, v2, vcc
	v_cndmask_b32_e32 v1, v1, v243, vcc
	v_cndmask_b32_e32 v3, v243, v3, vcc
	v_cvt_pk_bf16_f32 v244, v0, v1
	v_cvt_pk_bf16_f32 v245, v2, v3
	v_lshl_add_u64 v[248:249], v[4:5], 0, v[246:247]
	global_store_dwordx2 v[248:249], v[244:245], off
	s_nop 1
